# GLA-layer norm1 (with z projection): 7 of its 8 serialized parameter-load rounds turned into a 2-deep register ring carved from rematerialized LDS address registers; on top of norm-loop consolidation
# speedup vs baseline: 1.0041x; 1.0041x over previous
; __device__ __forceinline__ void unpack8(const v4u& w, float (&f)[8]) { f[0] = bflo(w.x); f[1] = bfhi(w.x); f[2] = bflo(w.y); f[3] = bfhi(w.y); f[4] = bflo(w.z); f[5] = bfhi(w.z); f[6] = bflo(w.w); f[7] = bfhi(w.w); }
; template <bool ZP, bool XF32, bool OUT8 = false>
; __device__ __forceinline__ void norm_phase(LAS unsigned char* lds, const void* xin, const float* gain, const float* sh, const float* sc, bf16* hout, const float* wzt, float* zout, int lane, int wave, int vcu, int G) {
;     ...
;         const int m0 = xdeal ? 2048 * (gw >> 8) + 2 * (gw & 255) + 512 * it_ : 2 * gw + it_ * 2 * NGW;
;         if (m0 >= M) break;
;         f32x4 v[2][4][2]; float ss[2] = {0.f, 0.f};
; #pragma unroll
;         for (int r = 0; r < 2; ++r)
; #pragma unroll
;             for (int j = 0; j < 4; ++j) {
;                 if constexpr (XF32) { const float* xr = (const float*)xin + (size_t)(m0 + r) * D + 8 * lane; v[r][j][0] = *(const f32x4*)(xr + 512 * j); v[r][j][1] = *(const f32x4*)(xr + 512 * j + 4); }
;                 else { float f[8]; unpack8(*(const v4u*)((const bf16*)xin + (size_t)(m0 + r) * D + 8 * lane + 512 * j), f); v[r][j][0] = (f32x4){f[0], f[1], f[2], f[3]}; v[r][j][1] = (f32x4){f[4], f[5], f[6], f[7]}; } }
; #pragma unroll
;         for (int r = 0; r < 2; ++r)
; #pragma unroll
;             for (int j = 0; j < 4; ++j)
; #pragma unroll
;                 for (int e = 0; e < 4; ++e) ss[r] += v[r][j][0][e] * v[r][j][0][e] + v[r][j][1][e] * v[r][j][1][e];
; #pragma unroll
;         for (int r = 0; r < 2; ++r) { const int m = m0 + r, b = m >> 11;
;             const float rstd = rsqrtf(wave_sum(ss[r]) * (1.0f / D) + EPS);
; #pragma unroll
;             for (int j = 0; j < 4; ++j) { const int col = 512 * j + 8 * lane;
; #pragma unroll
;                 for (int q = 0; q < 2; ++q) { const f32x4 gg = *(const f32x4*)(gain + col + 4 * q), s1 = *(const f32x4*)(sc + (size_t)b * MODW + col + 4 * q), s0 = *(const f32x4*)(sh + (size_t)b * MODW + col + 4 * q);
.LBB0_1557:
	s_ashr_i32 s19, s18, 31
	s_lshl_b64 s[24:25], s[18:19], 12
	s_add_i32 s20, s18, 1
	v_lshl_add_u64 v[2:3], v[58:59], 0, s[24:25]
	s_ashr_i32 s21, s20, 31
	global_load_dwordx4 v[18:21], v[2:3], off offset:1024
	global_load_dwordx4 v[10:13], v[2:3], off offset:3072
	global_load_dwordx4 v[14:17], v[2:3], off
	global_load_dwordx4 v[46:49], v[2:3], off offset:2048
	s_lshl_b64 s[22:23], s[20:21], 12
	s_waitcnt lgkmcnt(1)
	v_lshl_add_u64 v[6:7], v[58:59], 0, s[22:23]
	global_load_dwordx4 v[50:53], v[6:7], off offset:1024
	global_load_dwordx4 v[54:57], v[6:7], off
	global_load_dwordx4 v[2:5], v[6:7], off offset:3072
	global_load_dwordx4 v[74:77], v[6:7], off offset:2048
	s_ashr_i32 s0, s18, 11
	s_mul_hi_i32 s1, s0, 0xc000
	s_mul_i32 s0, s0, 0xc000
	s_add_u32 s26, s17, s0
	s_addc_u32 s27, s30, s1
	s_add_u32 s28, s31, s0
	s_addc_u32 s29, s34, s1
	v_and_b32_e32 v1, 64, v216
	v_add_u32_e32 v1, 64, v1
	s_ashr_i32 s0, s20, 11
	s_mul_hi_i32 s1, s0, 0xc000
	s_mul_i32 s0, s0, 0xc000
	s_waitcnt vmcnt(7)
	v_and_b32_e32 v7, 0xffff0000, v18
	s_waitcnt vmcnt(6)
	v_and_b32_e32 v40, 0xffff0000, v12
	v_lshlrev_b32_e32 v41, 16, v12
	v_and_b32_e32 v44, 0xffff0000, v13
	v_lshlrev_b32_e32 v45, 16, v13
	v_and_b32_e32 v38, 0xffff0000, v10
	v_lshlrev_b32_e32 v39, 16, v10
	v_and_b32_e32 v42, 0xffff0000, v11
	v_lshlrev_b32_e32 v43, 16, v11
	s_waitcnt vmcnt(5)
	v_lshlrev_b32_e32 v25, 16, v16
	v_and_b32_e32 v29, 0xffff0000, v16
	s_waitcnt vmcnt(4)
	v_lshlrev_b32_e32 v125, 16, v46
	v_and_b32_e32 v127, 0xffff0000, v46
	v_lshlrev_b32_e32 v129, 16, v47
	v_and_b32_e32 v131, 0xffff0000, v47
	v_lshlrev_b32_e32 v133, 16, v48
	v_and_b32_e32 v137, 0xffff0000, v48
	v_lshlrev_b32_e32 v135, 16, v49
	v_and_b32_e32 v139, 0xffff0000, v49
	v_pk_mul_f32 v[46:47], v[40:41], v[40:41]
	v_pk_mul_f32 v[48:49], v[44:45], v[44:45]
	s_waitcnt vmcnt(2)
	v_lshlrev_b32_e32 v24, 16, v56
	v_and_b32_e32 v28, 0xffff0000, v56
	v_lshlrev_b32_e32 v23, 16, v14
	v_and_b32_e32 v27, 0xffff0000, v14
	v_lshlrev_b32_e32 v31, 16, v17
	v_lshlrev_b32_e32 v22, 16, v54
	v_and_b32_e32 v26, 0xffff0000, v54
	v_lshlrev_b32_e32 v30, 16, v57
	v_pk_fma_f32 v[78:79], v[38:39], v[38:39], v[46:47]
	v_pk_fma_f32 v[88:89], v[42:43], v[42:43], v[48:49]
	v_pk_mul_f32 v[46:47], v[24:25], v[24:25]
	v_pk_mul_f32 v[48:49], v[28:29], v[28:29]
	v_lshlrev_b32_e32 v33, 16, v15
	v_and_b32_e32 v37, 0xffff0000, v17
	v_and_b32_e32 v6, 0xffff0000, v50
	v_lshlrev_b32_e32 v32, 16, v55
	v_and_b32_e32 v36, 0xffff0000, v57
	v_lshlrev_b32_e32 v10, 16, v50
	v_lshlrev_b32_e32 v14, 16, v51
	v_and_b32_e32 v16, 0xffff0000, v51
	v_pk_mul_f32 v[50:51], v[30:31], v[30:31]
	v_pk_fma_f32 v[46:47], v[22:23], v[22:23], v[46:47]
	v_pk_fma_f32 v[48:49], v[26:27], v[26:27], v[48:49]
	s_waitcnt lgkmcnt(0)
	v_and_b32_e32 v9, 0xffff0000, v20
	v_and_b32_e32 v35, 0xffff0000, v15
	v_lshlrev_b32_e32 v11, 16, v18
	v_lshlrev_b32_e32 v13, 16, v20
	v_and_b32_e32 v8, 0xffff0000, v52
	v_and_b32_e32 v34, 0xffff0000, v55
	v_lshlrev_b32_e32 v12, 16, v52
	v_lshlrev_b32_e32 v18, 16, v53
	v_and_b32_e32 v20, 0xffff0000, v53
	v_pk_mul_f32 v[52:53], v[36:37], v[36:37]
	v_pk_fma_f32 v[50:51], v[32:33], v[32:33], v[50:51]
	v_pk_add_f32 v[46:47], v[46:47], v[48:49]
	v_pk_fma_f32 v[48:49], v[34:35], v[34:35], v[52:53]
	v_pk_add_f32 v[46:47], v[50:51], v[46:47]
	v_lshlrev_b32_e32 v15, 16, v19
	v_pk_add_f32 v[46:47], v[48:49], v[46:47]
	v_pk_mul_f32 v[48:49], v[12:13], v[12:13]
	v_and_b32_e32 v17, 0xffff0000, v19
	v_pk_fma_f32 v[48:49], v[10:11], v[10:11], v[48:49]
	v_lshlrev_b32_e32 v19, 16, v21
	v_pk_add_f32 v[46:47], v[48:49], v[46:47]
	v_pk_mul_f32 v[48:49], v[8:9], v[8:9]
	v_and_b32_e32 v21, 0xffff0000, v21
	v_pk_fma_f32 v[48:49], v[6:7], v[6:7], v[48:49]
	s_waitcnt vmcnt(1)
	v_and_b32_e32 v140, 0xffff0000, v4
	v_pk_add_f32 v[46:47], v[48:49], v[46:47]
	v_pk_mul_f32 v[48:49], v[18:19], v[18:19]
	v_lshlrev_b32_e32 v141, 16, v4
	v_pk_fma_f32 v[48:49], v[14:15], v[14:15], v[48:49]
	s_waitcnt vmcnt(0)
	v_lshlrev_b32_e32 v132, 16, v76
	v_pk_add_f32 v[46:47], v[48:49], v[46:47]
	v_pk_mul_f32 v[48:49], v[20:21], v[20:21]
	v_and_b32_e32 v142, 0xffff0000, v2
	v_lshlrev_b32_e32 v143, 16, v2
	v_lshlrev_b32_e32 v124, 16, v74
	v_pk_mul_f32 v[54:55], v[140:141], v[140:141]
	v_pk_fma_f32 v[48:49], v[16:17], v[16:17], v[48:49]
	v_pk_mul_f32 v[56:57], v[132:133], v[132:133]
	v_and_b32_e32 v136, 0xffff0000, v76
	v_pk_fma_f32 v[90:91], v[142:143], v[142:143], v[54:55]
	v_pk_add_f32 v[54:55], v[48:49], v[46:47]
	v_pk_fma_f32 v[56:57], v[124:125], v[124:125], v[56:57]
	v_and_b32_e32 v126, 0xffff0000, v74
	v_pk_add_f32 v[54:55], v[56:57], v[54:55]
	v_pk_mul_f32 v[56:57], v[136:137], v[136:137]
	v_lshlrev_b32_e32 v134, 16, v77
	v_pk_fma_f32 v[56:57], v[126:127], v[126:127], v[56:57]
	v_lshlrev_b32_e32 v128, 16, v75
	v_pk_add_f32 v[54:55], v[56:57], v[54:55]
	v_pk_mul_f32 v[56:57], v[134:135], v[134:135]
	v_and_b32_e32 v138, 0xffff0000, v77
	v_pk_fma_f32 v[56:57], v[128:129], v[128:129], v[56:57]
	v_and_b32_e32 v130, 0xffff0000, v75
	v_pk_add_f32 v[54:55], v[56:57], v[54:55]
	v_pk_mul_f32 v[56:57], v[138:139], v[138:139]
	s_add_u32 s98, s17, s0
	s_addc_u32 s99, s30, s1
	s_add_u32 s100, s31, s0
	s_addc_u32 s101, s34, s1
	global_load_dwordx4 v[150:153], v213, s[26:27] offset:16
	global_load_dwordx4 v[154:157], v213, s[26:27]
	global_load_dwordx4 v[158:161], v[62:63], off offset:16
	global_load_dwordx4 v[162:165], v[62:63], off
	global_load_dwordx4 v[166:169], v213, s[28:29] offset:16
	global_load_dwordx4 v[170:173], v213, s[28:29]
	global_load_dwordx4 v[174:177], v[64:65], off
	global_load_dwordx4 v[178:181], v213, s[26:27] offset:2048
	global_load_dwordx4 v[182:185], v213, s[28:29] offset:2048
	global_load_dwordx4 v[186:189], v[64:65], off offset:16
	global_load_dwordx4 v[190:193], v213, s[26:27] offset:2064
	global_load_dwordx4 v[194:197], v213, s[28:29] offset:2064
	v_pk_fma_f32 v[56:57], v[130:131], v[130:131], v[56:57]
	v_and_b32_e32 v146, 0xffff0000, v5
	v_pk_add_f32 v[54:55], v[56:57], v[54:55]
	v_mov_b32_e32 v56, v91
	v_mov_b32_e32 v57, v79
	v_pk_add_f32 v[92:93], v[56:57], v[54:55]
	v_lshlrev_b32_e32 v147, 16, v5
	v_xor_b32_e32 v4, 1, v216
	v_and_b32_e32 v144, 0xffff0000, v3
	v_lshlrev_b32_e32 v145, 16, v3
	v_pk_mul_f32 v[2:3], v[146:147], v[146:147]
	v_cmp_lt_i32_e32 vcc, v4, v1
	v_pk_fma_f32 v[2:3], v[144:145], v[144:145], v[2:3]
	v_mov_b32_e32 v91, v78
	v_cndmask_b32_e32 v4, v216, v4, vcc
	v_lshlrev_b32_e32 v217, 2, v4
	v_pk_add_f32 v[4:5], v[90:91], v[92:93]
	v_mov_b32_e32 v78, v3
	v_mov_b32_e32 v79, v89
	v_pk_add_f32 v[4:5], v[78:79], v[4:5]
	v_mov_b32_e32 v3, v88
	v_pk_add_f32 v[2:3], v[2:3], v[4:5]
	ds_bpermute_b32 v5, v217, v3
	ds_bpermute_b32 v4, v217, v2
	v_xor_b32_e32 v78, 2, v216
	v_cmp_lt_i32_e32 vcc, v78, v1
	v_mov_b32_e32 v90, v23
	v_mov_b32_e32 v91, v27
	v_cndmask_b32_e32 v78, v216, v78, vcc
	v_lshlrev_b32_e32 v218, 2, v78
	s_waitcnt lgkmcnt(0)
; __device__ __forceinline__ unsigned pk2(float lo, float hi) { return f2bf(lo) | (f2bf(hi) << 16); }
; __device__ __forceinline__ float wave_sum(float v) {
; #pragma unroll
;     for (int o = 1; o < 64; o <<= 1) v += __shfl_xor(v, o);
;     return v;
; }
; template <bool ZP, bool XF32, bool OUT8 = false>
; __device__ __forceinline__ void norm_phase(LAS unsigned char* lds, const void* xin, const float* gain, const float* sh, const float* sc, bf16* hout, const float* wzt, float* zout, int lane, int wave, int vcu, int G) {
;     ...
;         for (int r = 0; r < 2; ++r) { const int m = m0 + r, b = m >> 11;
;             const float rstd = rsqrtf(wave_sum(ss[r]) * (1.0f / D) + EPS);
; #pragma unroll
;             for (int j = 0; j < 4; ++j) { const int col = 512 * j + 8 * lane;
; #pragma unroll
;                 for (int q = 0; q < 2; ++q) { const f32x4 gg = *(const f32x4*)(gain + col + 4 * q), s1 = *(const f32x4*)(sc + (size_t)b * MODW + col + 4 * q), s0 = *(const f32x4*)(sh + (size_t)b * MODW + col + 4 * q);
;                     v[r][j][q] = (v[r][j][q] * rstd * gg) * (s1 + 1.0f) + s0; }
;                 if constexpr (OUT8) { *(v2u*)((unsigned char*)hout + (size_t)m * D + col) = pack8_fp8(v[r][j][0][0], v[r][j][0][1], v[r][j][0][2], v[r][j][0][3], v[r][j][1][0], v[r][j][1][1], v[r][j][1][2], v[r][j][1][3], FP8_ASCALE); }
;                 else { v4u o; o.x = pk2(v[r][j][0][0], v[r][j][0][1]); o.y = pk2(v[r][j][0][2], v[r][j][0][3]); o.z = pk2(v[r][j][1][0], v[r][j][1][1]); o.w = pk2(v[r][j][1][2], v[r][j][1][3]);
;                     *(v4u*)(hout + (size_t)m * D + col) = o; } }
	v_pk_add_f32 v[2:3], v[2:3], v[4:5]
	ds_bpermute_b32 v5, v218, v3
	ds_bpermute_b32 v4, v218, v2
	v_xor_b32_e32 v78, 4, v216
	v_cmp_lt_i32_e32 vcc, v78, v1
	v_mov_b32_e32 v79, v35
	v_mov_b32_e32 v110, v133
	v_cndmask_b32_e32 v78, v216, v78, vcc
	v_lshlrev_b32_e32 v219, 2, v78
	s_waitcnt lgkmcnt(0)
	v_pk_add_f32 v[2:3], v[2:3], v[4:5]
	ds_bpermute_b32 v5, v219, v3
	ds_bpermute_b32 v4, v219, v2
	v_xor_b32_e32 v78, 8, v216
	v_cmp_lt_i32_e32 vcc, v78, v1
	v_mov_b32_e32 v111, v137
	v_mov_b32_e32 v108, v135
	v_cndmask_b32_e32 v78, v216, v78, vcc
	v_lshlrev_b32_e32 v220, 2, v78
	s_waitcnt lgkmcnt(0)
	v_pk_add_f32 v[2:3], v[2:3], v[4:5]
	ds_bpermute_b32 v5, v220, v3
	ds_bpermute_b32 v4, v220, v2
	v_xor_b32_e32 v78, 16, v216
	v_cmp_lt_i32_e32 vcc, v78, v1
	v_mov_b32_e32 v109, v139
	v_pk_mov_b32 v[42:43], v[42:43], v[42:43] op_sel:[1,0]
	v_cndmask_b32_e32 v78, v216, v78, vcc
	v_lshlrev_b32_e32 v221, 2, v78
	s_waitcnt lgkmcnt(0)
	v_pk_add_f32 v[2:3], v[2:3], v[4:5]
	ds_bpermute_b32 v5, v221, v3
	ds_bpermute_b32 v4, v221, v2
	v_xor_b32_e32 v78, 32, v216
	v_cmp_lt_i32_e32 vcc, v78, v1
	v_pk_mov_b32 v[44:45], v[44:45], v[44:45] op_sel:[1,0]
	v_mov_b32_e32 v23, v26
	v_cndmask_b32_e32 v1, v216, v78, vcc
	v_lshlrev_b32_e32 v222, 2, v1
	s_waitcnt lgkmcnt(0)
	v_pk_add_f32 v[2:3], v[2:3], v[4:5]
	ds_bpermute_b32 v5, v222, v3
	ds_bpermute_b32 v4, v222, v2
	v_mov_b32_e32 v78, v33
	v_mov_b32_e32 v33, v34
	v_mov_b32_e32 v135, v138
	v_mov_b32_e32 v133, v136
	s_waitcnt lgkmcnt(0)
	v_pk_add_f32 v[2:3], v[2:3], v[4:5]
	v_lshl_add_u64 v[4:5], v[70:71], 0, s[24:25]
	v_pk_fma_f32 v[2:3], v[2:3], s[16:17], v[72:73] op_sel_hi:[1,0,0]
	s_add_u32 s24, s17, s0
	v_mul_f32_e32 v1, 0x4b800000, v3
	v_cmp_gt_f32_e32 vcc, s40, v3
	s_waitcnt vmcnt(6)
	s_nop 1
	v_mov_b64_e32 v[46:47], v[150:151]
	v_mov_b64_e32 v[48:49], v[152:153]
	v_mov_b64_e32 v[50:51], v[154:155]
	v_mov_b64_e32 v[52:53], v[156:157]
	v_mov_b64_e32 v[54:55], v[158:159]
	v_mov_b64_e32 v[56:57], v[160:161]
	v_mov_b64_e32 v[74:75], v[162:163]
	v_mov_b64_e32 v[76:77], v[164:165]
	v_mov_b64_e32 v[80:81], v[166:167]
	v_mov_b64_e32 v[82:83], v[168:169]
	v_mov_b64_e32 v[84:85], v[170:171]
	v_mov_b64_e32 v[86:87], v[172:173]
	global_load_dwordx4 v[150:153], v[66:67], off
	global_load_dwordx4 v[154:157], v214, s[26:27]
	global_load_dwordx4 v[158:161], v214, s[28:29]
	global_load_dwordx4 v[162:165], v[66:67], off offset:16
	global_load_dwordx4 v[166:169], v214, s[26:27] offset:16
	global_load_dwordx4 v[170:173], v214, s[28:29] offset:16
	v_pk_add_f32 v[88:89], v[46:47], 1.0 op_sel_hi:[1,0]
	v_pk_add_f32 v[50:51], v[50:51], 1.0 op_sel_hi:[1,0]
	v_cndmask_b32_e32 v1, v3, v1, vcc
	v_rsq_f32_e32 v1, v1
	v_pk_add_f32 v[52:53], v[52:53], 1.0 op_sel_hi:[1,0]
	v_pk_add_f32 v[48:49], v[48:49], 1.0 op_sel_hi:[1,0]
	s_addc_u32 s25, s30, s1
	v_mul_f32_e32 v3, 0x45800000, v1
	v_cndmask_b32_e32 v46, v1, v3, vcc
	v_pk_mul_f32 v[90:91], v[46:47], v[90:91] op_sel_hi:[0,1]
	v_pk_mul_f32 v[78:79], v[46:47], v[78:79] op_sel_hi:[0,1]
	v_pk_mul_f32 v[90:91], v[74:75], v[90:91]
	v_pk_mul_f32 v[74:75], v[76:77], v[78:79]
	v_pk_fma_f32 v[78:79], v[50:51], v[90:91], v[84:85]
	v_mov_b32_e32 v50, v31
	v_mov_b32_e32 v51, v37
	v_bfe_u32 v1, v78, 16, 1
	v_pk_mul_f32 v[50:51], v[46:47], v[50:51] op_sel_hi:[0,1]
	v_add3_u32 v1, v78, v1, s41
	v_bfe_u32 v3, v79, 16, 1
	v_pk_fma_f32 v[74:75], v[52:53], v[74:75], v[86:87]
	v_mov_b32_e32 v52, v25
	v_mov_b32_e32 v53, v29
	v_pk_mul_f32 v[50:51], v[56:57], v[50:51]
	v_lshrrev_b32_e32 v1, 16, v1
	v_add3_u32 v3, v79, v3, s41
	v_pk_mul_f32 v[52:53], v[46:47], v[52:53] op_sel_hi:[0,1]
	v_pk_fma_f32 v[76:77], v[48:49], v[50:51], v[82:83]
	v_and_or_b32 v48, v3, s39, v1
	v_bfe_u32 v1, v74, 16, 1
	v_pk_mul_f32 v[52:53], v[54:55], v[52:53]
	v_add3_u32 v1, v74, v1, s41
	v_bfe_u32 v3, v75, 16, 1
	v_pk_fma_f32 v[82:83], v[88:89], v[52:53], v[80:81]
	v_lshrrev_b32_e32 v1, 16, v1
	v_add3_u32 v3, v75, v3, s41
	v_and_or_b32 v49, v3, s39, v1
	v_bfe_u32 v1, v82, 16, 1
	v_add3_u32 v1, v82, v1, s41
	v_bfe_u32 v3, v83, 16, 1
	v_lshrrev_b32_e32 v1, 16, v1
	v_add3_u32 v3, v83, v3, s41
	v_and_or_b32 v50, v3, s39, v1
	v_bfe_u32 v1, v76, 16, 1
	v_add3_u32 v1, v76, v1, s41
	v_bfe_u32 v3, v77, 16, 1
	v_lshrrev_b32_e32 v1, 16, v1
	v_add3_u32 v3, v77, v3, s41
	v_and_or_b32 v51, v3, s39, v1
	global_store_dwordx4 v[4:5], v[48:51], off
	s_nop 0
	v_mov_b32_e32 v80, v11
	v_mov_b32_e32 v81, v7
	v_pk_mul_f32 v[80:81], v[46:47], v[80:81] op_sel_hi:[0,1]
	v_mov_b32_e32 v56, v15
	v_mov_b32_e32 v57, v17
	v_pk_mul_f32 v[56:57], v[46:47], v[56:57] op_sel_hi:[0,1]
	v_pk_mul_f32 v[108:109], v[46:47], v[108:109] op_sel_hi:[0,1]
	v_pk_mul_f32 v[44:45], v[46:47], v[44:45] op_sel_hi:[0,1]
	v_cmp_gt_f32_e32 vcc, s40, v2
	v_mov_b32_e32 v31, v36
	v_mov_b32_e32 v25, v28
	v_mov_b32_e32 v136, v143
	v_mov_b32_e32 v137, v142
	v_mov_b32_e32 v138, v141
	v_mov_b32_e32 v139, v140
	v_pk_mov_b32 v[144:145], v[144:145], v[144:145] op_sel:[1,0]
	v_pk_mov_b32 v[146:147], v[146:147], v[146:147] op_sel:[1,0]
	s_waitcnt vmcnt(6)
; __device__ __forceinline__ unsigned pk2(float lo, float hi) { return f2bf(lo) | (f2bf(hi) << 16); }
; template <bool ZP, bool XF32, bool OUT8 = false>
; __device__ __forceinline__ void norm_phase(LAS unsigned char* lds, const void* xin, const float* gain, const float* sh, const float* sc, bf16* hout, const float* wzt, float* zout, int lane, int wave, int vcu, int G) {
;     ...
;             for (int j = 0; j < 4; ++j) { const int col = 512 * j + 8 * lane;
; #pragma unroll
;                 for (int q = 0; q < 2; ++q) { const f32x4 gg = *(const f32x4*)(gain + col + 4 * q), s1 = *(const f32x4*)(sc + (size_t)b * MODW + col + 4 * q), s0 = *(const f32x4*)(sh + (size_t)b * MODW + col + 4 * q);
;                     v[r][j][q] = (v[r][j][q] * rstd * gg) * (s1 + 1.0f) + s0; }
;                 if constexpr (OUT8) { *(v2u*)((unsigned char*)hout + (size_t)m * D + col) = pack8_fp8(v[r][j][0][0], v[r][j][0][1], v[r][j][0][2], v[r][j][0][3], v[r][j][1][0], v[r][j][1][1], v[r][j][1][2], v[r][j][1][3], FP8_ASCALE); }
;                 else { v4u o; o.x = pk2(v[r][j][0][0], v[r][j][0][1]); o.y = pk2(v[r][j][0][2], v[r][j][0][3]); o.z = pk2(v[r][j][1][0], v[r][j][1][1]); o.w = pk2(v[r][j][1][2], v[r][j][1][3]);
;                     *(v4u*)(hout + (size_t)m * D + col) = o; } }
	s_nop 1
	v_mov_b64_e32 v[48:49], v[174:175]
	v_mov_b64_e32 v[50:51], v[176:177]
	v_mov_b64_e32 v[52:53], v[178:179]
	v_mov_b64_e32 v[54:55], v[180:181]
	v_mov_b64_e32 v[84:85], v[182:183]
	v_mov_b64_e32 v[86:87], v[184:185]
	v_mov_b64_e32 v[88:89], v[186:187]
	v_mov_b64_e32 v[90:91], v[188:189]
	v_mov_b64_e32 v[92:93], v[190:191]
	v_mov_b64_e32 v[94:95], v[192:193]
	v_mov_b64_e32 v[96:97], v[194:195]
	v_mov_b64_e32 v[98:99], v[196:197]
	global_load_dwordx4 v[174:177], v[68:69], off
	global_load_dwordx4 v[178:181], v215, s[26:27]
	global_load_dwordx4 v[182:185], v[68:69], off offset:16
	global_load_dwordx4 v[186:189], v215, s[26:27] offset:16
	global_load_dwordx4 v[190:193], v215, s[28:29]
	global_load_dwordx4 v[194:197], v215, s[28:29] offset:16
	v_pk_mul_f32 v[48:49], v[48:49], v[80:81]
	v_pk_add_f32 v[52:53], v[52:53], 1.0 op_sel_hi:[1,0]
	v_pk_mul_f32 v[50:51], v[50:51], v[56:57]
	v_pk_fma_f32 v[84:85], v[52:53], v[48:49], v[84:85]
	v_mov_b32_e32 v48, v19
	v_mov_b32_e32 v49, v21
	v_bfe_u32 v1, v84, 16, 1
	v_pk_add_f32 v[54:55], v[54:55], 1.0 op_sel_hi:[1,0]
	v_pk_mul_f32 v[48:49], v[46:47], v[48:49] op_sel_hi:[0,1]
	v_add3_u32 v1, v84, v1, s41
	v_bfe_u32 v3, v85, 16, 1
	v_pk_fma_f32 v[80:81], v[54:55], v[50:51], v[86:87]
	v_mov_b32_e32 v50, v13
	v_mov_b32_e32 v51, v9
	v_pk_mul_f32 v[48:49], v[90:91], v[48:49]
	v_pk_add_f32 v[52:53], v[94:95], 1.0 op_sel_hi:[1,0]
	v_lshrrev_b32_e32 v1, 16, v1
	v_add3_u32 v3, v85, v3, s41
	v_pk_mul_f32 v[50:51], v[46:47], v[50:51] op_sel_hi:[0,1]
	v_pk_fma_f32 v[86:87], v[52:53], v[48:49], v[98:99]
	v_and_or_b32 v48, v3, s39, v1
	v_bfe_u32 v1, v80, 16, 1
	v_pk_mul_f32 v[50:51], v[88:89], v[50:51]
	v_pk_add_f32 v[54:55], v[92:93], 1.0 op_sel_hi:[1,0]
	v_add3_u32 v1, v80, v1, s41
	v_bfe_u32 v3, v81, 16, 1
	v_pk_fma_f32 v[88:89], v[54:55], v[50:51], v[96:97]
	v_lshrrev_b32_e32 v1, 16, v1
	v_add3_u32 v3, v81, v3, s41
	v_and_or_b32 v49, v3, s39, v1
	v_bfe_u32 v1, v88, 16, 1
	v_add3_u32 v1, v88, v1, s41
	v_bfe_u32 v3, v89, 16, 1
	v_lshrrev_b32_e32 v1, 16, v1
	v_add3_u32 v3, v89, v3, s41
	v_and_or_b32 v50, v3, s39, v1
	v_bfe_u32 v1, v86, 16, 1
	v_add3_u32 v1, v86, v1, s41
	v_bfe_u32 v3, v87, 16, 1
	v_lshrrev_b32_e32 v1, 16, v1
	v_add3_u32 v3, v87, v3, s41
	v_and_or_b32 v51, v3, s39, v1
	global_store_dwordx4 v[4:5], v[48:51], off offset:1024
	s_nop 0
	v_mov_b32_e32 v56, v129
	v_mov_b32_e32 v57, v131
	v_mov_b32_e32 v90, v125
	v_mov_b32_e32 v91, v127
	v_pk_mul_f32 v[56:57], v[46:47], v[56:57] op_sel_hi:[0,1]
	v_pk_mul_f32 v[90:91], v[46:47], v[90:91] op_sel_hi:[0,1]
	v_mov_b32_e32 v19, v20
	v_mov_b32_e32 v129, v130
	v_mov_b32_e32 v125, v126
	s_waitcnt vmcnt(6)
	s_nop 1
	v_mov_b64_e32 v[48:49], v[150:151]
	v_mov_b64_e32 v[50:51], v[152:153]
	v_mov_b64_e32 v[52:53], v[154:155]
	v_mov_b64_e32 v[54:55], v[156:157]
	v_mov_b64_e32 v[92:93], v[158:159]
	v_mov_b64_e32 v[94:95], v[160:161]
	v_mov_b64_e32 v[96:97], v[162:163]
	v_mov_b64_e32 v[98:99], v[164:165]
	v_mov_b64_e32 v[100:101], v[166:167]
	v_mov_b64_e32 v[102:103], v[168:169]
	v_mov_b64_e32 v[104:105], v[170:171]
	v_mov_b64_e32 v[106:107], v[172:173]
	global_load_dwordx4 v[150:153], v[62:63], off
	global_load_dwordx4 v[154:157], v213, s[98:99]
	global_load_dwordx4 v[158:161], v[62:63], off offset:16
	global_load_dwordx4 v[162:165], v213, s[98:99] offset:16
	global_load_dwordx4 v[166:169], v213, s[100:101]
	global_load_dwordx4 v[170:173], v213, s[100:101] offset:16
	v_pk_mul_f32 v[48:49], v[48:49], v[90:91]
	v_pk_mul_f32 v[50:51], v[50:51], v[56:57]
	v_pk_add_f32 v[54:55], v[54:55], 1.0 op_sel_hi:[1,0]
	v_pk_add_f32 v[52:53], v[52:53], 1.0 op_sel_hi:[1,0]
	v_pk_fma_f32 v[90:91], v[54:55], v[50:51], v[94:95]
	v_pk_fma_f32 v[94:95], v[52:53], v[48:49], v[92:93]
	v_pk_mul_f32 v[48:49], v[46:47], v[110:111] op_sel_hi:[0,1]
	v_bfe_u32 v1, v94, 16, 1
	v_add3_u32 v1, v94, v1, s41
	v_bfe_u32 v3, v95, 16, 1
	v_pk_mul_f32 v[48:49], v[96:97], v[48:49]
	v_pk_add_f32 v[54:55], v[100:101], 1.0 op_sel_hi:[1,0]
	v_lshrrev_b32_e32 v1, 16, v1
	v_add3_u32 v3, v95, v3, s41
	v_pk_fma_f32 v[96:97], v[54:55], v[48:49], v[104:105]
	v_and_or_b32 v48, v3, s39, v1
	v_bfe_u32 v1, v90, 16, 1
	v_add3_u32 v1, v90, v1, s41
	v_bfe_u32 v3, v91, 16, 1
	v_lshrrev_b32_e32 v1, 16, v1
	v_add3_u32 v3, v91, v3, s41
	v_and_or_b32 v49, v3, s39, v1
	v_bfe_u32 v1, v96, 16, 1
	v_pk_mul_f32 v[50:51], v[98:99], v[108:109]
	v_pk_add_f32 v[52:53], v[102:103], 1.0 op_sel_hi:[1,0]
	v_add3_u32 v1, v96, v1, s41
	v_bfe_u32 v3, v97, 16, 1
	v_pk_fma_f32 v[92:93], v[52:53], v[50:51], v[106:107]
	v_lshrrev_b32_e32 v1, 16, v1
	v_add3_u32 v3, v97, v3, s41
	v_and_or_b32 v50, v3, s39, v1
	v_bfe_u32 v1, v92, 16, 1
	v_add3_u32 v1, v92, v1, s41
	v_bfe_u32 v3, v93, 16, 1
	v_lshrrev_b32_e32 v1, 16, v1
	v_add3_u32 v3, v93, v3, s41
	v_and_or_b32 v51, v3, s39, v1
	global_store_dwordx4 v[4:5], v[48:51], off offset:2048
	s_nop 0
	v_mov_b32_e32 v56, v39
	v_mov_b32_e32 v57, v38
	v_mov_b32_e32 v38, v41
	v_mov_b32_e32 v39, v40
	v_pk_mul_f32 v[40:41], v[46:47], v[42:43] op_sel_hi:[0,1]
	v_pk_mul_f32 v[42:43], v[46:47], v[56:57] op_sel_hi:[0,1]
	v_pk_mul_f32 v[38:39], v[46:47], v[38:39] op_sel_hi:[0,1]
	s_add_u32 s26, s31, s0
	s_addc_u32 s27, s34, s1
	s_waitcnt vmcnt(6)
; __device__ __forceinline__ unsigned pk2(float lo, float hi) { return f2bf(lo) | (f2bf(hi) << 16); }
; template <bool ZP, bool XF32, bool OUT8 = false>
; __device__ __forceinline__ void norm_phase(LAS unsigned char* lds, const void* xin, const float* gain, const float* sh, const float* sc, bf16* hout, const float* wzt, float* zout, int lane, int wave, int vcu, int G) {
;     ...
;         for (int r = 0; r < 2; ++r) { const int m = m0 + r, b = m >> 11;
;             const float rstd = rsqrtf(wave_sum(ss[r]) * (1.0f / D) + EPS);
; #pragma unroll
;             for (int j = 0; j < 4; ++j) { const int col = 512 * j + 8 * lane;
; #pragma unroll
;                 for (int q = 0; q < 2; ++q) { const f32x4 gg = *(const f32x4*)(gain + col + 4 * q), s1 = *(const f32x4*)(sc + (size_t)b * MODW + col + 4 * q), s0 = *(const f32x4*)(sh + (size_t)b * MODW + col + 4 * q);
;                     v[r][j][q] = (v[r][j][q] * rstd * gg) * (s1 + 1.0f) + s0; }
;                 if constexpr (OUT8) { *(v2u*)((unsigned char*)hout + (size_t)m * D + col) = pack8_fp8(v[r][j][0][0], v[r][j][0][1], v[r][j][0][2], v[r][j][0][3], v[r][j][1][0], v[r][j][1][1], v[r][j][1][2], v[r][j][1][3], FP8_ASCALE); }
;                 else { v4u o; o.x = pk2(v[r][j][0][0], v[r][j][0][1]); o.y = pk2(v[r][j][0][2], v[r][j][0][3]); o.z = pk2(v[r][j][1][0], v[r][j][1][1]); o.w = pk2(v[r][j][1][2], v[r][j][1][3]);
;                     *(v4u*)(hout + (size_t)m * D + col) = o; } }
	s_nop 1
	v_mov_b64_e32 v[48:49], v[174:175]
	v_mov_b64_e32 v[50:51], v[176:177]
	v_mov_b64_e32 v[52:53], v[178:179]
	v_mov_b64_e32 v[54:55], v[180:181]
	v_mov_b64_e32 v[98:99], v[182:183]
	v_mov_b64_e32 v[100:101], v[184:185]
	v_mov_b64_e32 v[102:103], v[186:187]
	v_mov_b64_e32 v[104:105], v[188:189]
	v_mov_b64_e32 v[106:107], v[190:191]
	v_mov_b64_e32 v[108:109], v[192:193]
	v_mov_b64_e32 v[110:111], v[194:195]
	v_mov_b64_e32 v[112:113], v[196:197]
	global_load_dwordx4 v[174:177], v[64:65], off
	global_load_dwordx4 v[178:181], v213, s[98:99] offset:2048
	global_load_dwordx4 v[182:185], v[64:65], off offset:16
	global_load_dwordx4 v[186:189], v213, s[98:99] offset:2064
	global_load_dwordx4 v[190:193], v213, s[100:101] offset:2048
	global_load_dwordx4 v[194:197], v213, s[100:101] offset:2064
	v_pk_mul_f32 v[42:43], v[48:49], v[42:43]
	v_pk_mul_f32 v[40:41], v[50:51], v[40:41]
	v_pk_add_f32 v[46:47], v[54:55], 1.0 op_sel_hi:[1,0]
	v_pk_add_f32 v[48:49], v[52:53], 1.0 op_sel_hi:[1,0]
	v_pk_mul_f32 v[38:39], v[38:39], v[98:99]
	v_pk_mul_f32 v[44:45], v[44:45], v[100:101]
	v_pk_add_f32 v[50:51], v[104:105], 1.0 op_sel_hi:[1,0]
	v_pk_add_f32 v[52:53], v[102:103], 1.0 op_sel_hi:[1,0]
	v_pk_fma_f32 v[100:101], v[40:41], v[46:47], v[108:109]
	v_pk_fma_f32 v[104:105], v[42:43], v[48:49], v[106:107]
	v_pk_fma_f32 v[102:103], v[44:45], v[50:51], v[112:113]
	v_pk_fma_f32 v[106:107], v[38:39], v[52:53], v[110:111]
	v_bfe_u32 v1, v104, 16, 1
	v_bfe_u32 v7, v100, 16, 1
	v_bfe_u32 v11, v106, 16, 1
	v_bfe_u32 v15, v102, 16, 1
	v_bfe_u32 v3, v105, 16, 1
	v_bfe_u32 v9, v101, 16, 1
	v_bfe_u32 v13, v107, 16, 1
	v_bfe_u32 v17, v103, 16, 1
	v_add3_u32 v1, v104, v1, s41
	v_add3_u32 v7, v100, v7, s41
	v_add3_u32 v11, v106, v11, s41
	v_add3_u32 v15, v102, v15, s41
	v_add3_u32 v3, v105, v3, s41
	v_add3_u32 v9, v101, v9, s41
	v_add3_u32 v13, v107, v13, s41
	v_add3_u32 v17, v103, v17, s41
	v_lshrrev_b32_e32 v1, 16, v1
	v_lshrrev_b32_e32 v7, 16, v7
	v_lshrrev_b32_e32 v11, 16, v11
	v_lshrrev_b32_e32 v15, 16, v15
	v_and_or_b32 v38, v3, s39, v1
	v_and_or_b32 v39, v9, s39, v7
	v_and_or_b32 v40, v13, s39, v11
	v_and_or_b32 v41, v17, s39, v15
	global_store_dwordx4 v[4:5], v[38:41], off offset:3072
	s_nop 0
	v_mul_f32_e32 v1, 0x4b800000, v2
	v_cndmask_b32_e32 v1, v2, v1, vcc
	v_rsq_f32_e32 v1, v1
	v_lshl_add_u64 v[98:99], v[70:71], 0, s[22:23]
	v_mov_b32_e32 v13, v8
	v_mov_b32_e32 v15, v16
	v_mul_f32_e32 v2, 0x45800000, v1
	v_cndmask_b32_e32 v148, v1, v2, vcc
	v_pk_mul_f32 v[2:3], v[148:149], v[32:33] op_sel_hi:[0,1]
	v_pk_mul_f32 v[4:5], v[148:149], v[22:23] op_sel_hi:[0,1]
	v_pk_mul_f32 v[22:23], v[148:149], v[30:31] op_sel_hi:[0,1]
	v_pk_mul_f32 v[24:25], v[148:149], v[24:25] op_sel_hi:[0,1]
	v_pk_mul_f32 v[12:13], v[148:149], v[12:13] op_sel_hi:[0,1]
	v_pk_mul_f32 v[126:127], v[148:149], v[128:129] op_sel_hi:[0,1]
	v_pk_mul_f32 v[124:125], v[148:149], v[124:125] op_sel_hi:[0,1]
	v_pk_mul_f32 v[128:129], v[148:149], v[134:135] op_sel_hi:[0,1]
	v_pk_mul_f32 v[130:131], v[148:149], v[132:133] op_sel_hi:[0,1]
	v_pk_mul_f32 v[242:243], v[148:149], v[136:137] op_sel_hi:[0,1]
	v_pk_mul_f32 v[246:247], v[148:149], v[138:139] op_sel_hi:[0,1]
	v_pk_mul_f32 v[240:241], v[148:149], v[144:145] op_sel_hi:[0,1]
	v_pk_mul_f32 v[244:245], v[148:149], v[146:147] op_sel_hi:[0,1]
	s_waitcnt vmcnt(6)
	s_nop 1
	v_mov_b64_e32 v[38:39], v[150:151]
	v_mov_b64_e32 v[40:41], v[152:153]
	v_mov_b64_e32 v[42:43], v[154:155]
	v_mov_b64_e32 v[44:45], v[156:157]
	v_mov_b64_e32 v[46:47], v[158:159]
	v_mov_b64_e32 v[48:49], v[160:161]
	v_mov_b64_e32 v[50:51], v[162:163]
	v_mov_b64_e32 v[52:53], v[164:165]
	v_mov_b64_e32 v[54:55], v[166:167]
	v_mov_b64_e32 v[56:57], v[168:169]
	v_mov_b64_e32 v[114:115], v[170:171]
	v_mov_b64_e32 v[116:117], v[172:173]
	global_load_dwordx4 v[150:153], v[66:67], off
	global_load_dwordx4 v[154:157], v214, s[98:99]
	global_load_dwordx4 v[158:161], v[66:67], off offset:16
	global_load_dwordx4 v[162:165], v214, s[98:99] offset:16
	global_load_dwordx4 v[166:169], v214, s[100:101] offset:16
	global_load_dwordx4 v[170:173], v214, s[100:101]
	v_pk_add_f32 v[26:27], v[44:45], 1.0 op_sel_hi:[1,0]
	v_pk_mul_f32 v[4:5], v[38:39], v[4:5]
	v_pk_mul_f32 v[2:3], v[40:41], v[2:3]
	v_pk_add_f32 v[28:29], v[42:43], 1.0 op_sel_hi:[1,0]
	v_pk_mul_f32 v[24:25], v[46:47], v[24:25]
	v_pk_mul_f32 v[22:23], v[48:49], v[22:23]
	v_pk_add_f32 v[30:31], v[52:53], 1.0 op_sel_hi:[1,0]
	v_pk_add_f32 v[32:33], v[50:51], 1.0 op_sel_hi:[1,0]
	v_pk_fma_f32 v[108:109], v[26:27], v[2:3], v[56:57]
	v_pk_fma_f32 v[112:113], v[28:29], v[4:5], v[54:55]
	v_pk_fma_f32 v[110:111], v[30:31], v[22:23], v[116:117]
	v_pk_fma_f32 v[114:115], v[32:33], v[24:25], v[114:115]
	v_bfe_u32 v1, v112, 16, 1
	v_bfe_u32 v3, v108, 16, 1
	v_bfe_u32 v5, v114, 16, 1
	v_bfe_u32 v9, v110, 16, 1
	v_bfe_u32 v2, v113, 16, 1
	v_bfe_u32 v4, v109, 16, 1
	v_bfe_u32 v7, v115, 16, 1
	v_bfe_u32 v11, v111, 16, 1
	v_add3_u32 v1, v112, v1, s41
	v_add3_u32 v3, v108, v3, s41
	v_add3_u32 v5, v114, v5, s41
	v_add3_u32 v9, v110, v9, s41
	v_add3_u32 v2, v113, v2, s41
	v_add3_u32 v4, v109, v4, s41
	v_add3_u32 v7, v115, v7, s41
	v_add3_u32 v11, v111, v11, s41
	v_lshrrev_b32_e32 v1, 16, v1
	v_lshrrev_b32_e32 v3, 16, v3
	v_lshrrev_b32_e32 v5, 16, v5
	v_lshrrev_b32_e32 v9, 16, v9
	v_and_or_b32 v2, v2, s39, v1
	v_and_or_b32 v3, v4, s39, v3
	v_and_or_b32 v4, v7, s39, v5
	v_and_or_b32 v5, v11, s39, v9
	global_store_dwordx4 v[98:99], v[2:5], off
	s_nop 0
	v_mov_b32_e32 v11, v6
	v_pk_mul_f32 v[6:7], v[148:149], v[14:15] op_sel_hi:[0,1]
	v_pk_mul_f32 v[8:9], v[148:149], v[10:11] op_sel_hi:[0,1]
	v_pk_mul_f32 v[10:11], v[148:149], v[18:19] op_sel_hi:[0,1]
	s_waitcnt vmcnt(6)
; #define LAS __attribute__((address_space(3)))
; __device__ __forceinline__ unsigned pk2(float lo, float hi) { return f2bf(lo) | (f2bf(hi) << 16); }
; template <bool ZP, bool XF32, bool OUT8 = false>
; __device__ __forceinline__ void norm_phase(LAS unsigned char* lds, const void* xin, const float* gain, const float* sh, const float* sc, bf16* hout, const float* wzt, float* zout, int lane, int wave, int vcu, int G) {
;     ...
;             for (int j = 0; j < 4; ++j) { const int col = 512 * j + 8 * lane;
; #pragma unroll
;                 for (int q = 0; q < 2; ++q) { const f32x4 gg = *(const f32x4*)(gain + col + 4 * q), s1 = *(const f32x4*)(sc + (size_t)b * MODW + col + 4 * q), s0 = *(const f32x4*)(sh + (size_t)b * MODW + col + 4 * q);
;                     v[r][j][q] = (v[r][j][q] * rstd * gg) * (s1 + 1.0f) + s0; }
;                 if constexpr (OUT8) { *(v2u*)((unsigned char*)hout + (size_t)m * D + col) = pack8_fp8(v[r][j][0][0], v[r][j][0][1], v[r][j][0][2], v[r][j][0][3], v[r][j][1][0], v[r][j][1][1], v[r][j][1][2], v[r][j][1][3], FP8_ASCALE); }
;                 else { v4u o; o.x = pk2(v[r][j][0][0], v[r][j][0][1]); o.y = pk2(v[r][j][0][2], v[r][j][0][3]); o.z = pk2(v[r][j][1][0], v[r][j][1][1]); o.w = pk2(v[r][j][1][2], v[r][j][1][3]);
;                     *(v4u*)(hout + (size_t)m * D + col) = o; } }
;         }
;         if constexpr (ZP) {
;             float p0[16], p1[16];
; #pragma unroll
;             for (int rr = 0; rr < 16; ++rr) { p0[rr] = 0.f; p1[rr] = 0.f;
; #pragma unroll
;                 for (int j = 0; j < 4; ++j) { const f32x4 w0 = *(const LAS f32x4*)(wl + (((rr * 4 + j) * 2 + 0) * 64 + lane) * 4), w1 = *(const LAS f32x4*)(wl + (((rr * 4 + j) * 2 + 1) * 64 + lane) * 4);
; #pragma unroll
;                     for (int e = 0; e < 4; ++e) { p0[rr] += v[0][j][0][e] * w0[e] + v[0][j][1][e] * w1[e]; p1[rr] += v[1][j][0][e] * w0[e] + v[1][j][1][e] * w1[e]; } } }
	s_nop 1
	v_mov_b64_e32 v[2:3], v[174:175]
	v_mov_b64_e32 v[4:5], v[176:177]
	v_mov_b64_e32 v[22:23], v[178:179]
	v_mov_b64_e32 v[24:25], v[180:181]
	v_mov_b64_e32 v[26:27], v[182:183]
	v_mov_b64_e32 v[28:29], v[184:185]
	v_mov_b64_e32 v[30:31], v[186:187]
	v_mov_b64_e32 v[32:33], v[188:189]
	v_mov_b64_e32 v[34:35], v[190:191]
	v_mov_b64_e32 v[36:37], v[192:193]
	v_mov_b64_e32 v[38:39], v[194:195]
	v_mov_b64_e32 v[40:41], v[196:197]
	v_pk_mul_f32 v[2:3], v[2:3], v[8:9]
	v_pk_mul_f32 v[4:5], v[4:5], v[6:7]
	v_pk_add_f32 v[6:7], v[24:25], 1.0 op_sel_hi:[1,0]
	v_pk_add_f32 v[8:9], v[22:23], 1.0 op_sel_hi:[1,0]
	v_pk_mul_f32 v[12:13], v[26:27], v[12:13]
	v_pk_mul_f32 v[10:11], v[28:29], v[10:11]
	v_pk_add_f32 v[14:15], v[32:33], 1.0 op_sel_hi:[1,0]
	v_pk_add_f32 v[16:17], v[30:31], 1.0 op_sel_hi:[1,0]
	v_pk_fma_f32 v[116:117], v[6:7], v[4:5], v[36:37]
	v_pk_fma_f32 v[120:121], v[8:9], v[2:3], v[34:35]
	v_pk_fma_f32 v[118:119], v[14:15], v[10:11], v[40:41]
	v_pk_fma_f32 v[122:123], v[16:17], v[12:13], v[38:39]
	v_bfe_u32 v1, v120, 16, 1
	v_bfe_u32 v3, v116, 16, 1
	v_bfe_u32 v5, v122, 16, 1
	v_bfe_u32 v7, v118, 16, 1
	v_bfe_u32 v2, v121, 16, 1
	v_bfe_u32 v4, v117, 16, 1
	v_bfe_u32 v6, v123, 16, 1
	v_bfe_u32 v8, v119, 16, 1
	v_add3_u32 v1, v120, v1, s41
	v_add3_u32 v3, v116, v3, s41
	v_add3_u32 v5, v122, v5, s41
	v_add3_u32 v7, v118, v7, s41
	v_add3_u32 v2, v121, v2, s41
	v_add3_u32 v4, v117, v4, s41
	v_add3_u32 v6, v123, v6, s41
	v_add3_u32 v8, v119, v8, s41
	v_lshrrev_b32_e32 v1, 16, v1
	v_lshrrev_b32_e32 v3, 16, v3
	v_lshrrev_b32_e32 v5, 16, v5
	v_lshrrev_b32_e32 v7, 16, v7
	v_and_or_b32 v2, v2, s39, v1
	v_and_or_b32 v3, v4, s39, v3
	v_and_or_b32 v4, v6, s39, v5
	v_and_or_b32 v5, v8, s39, v7
	global_store_dwordx4 v[98:99], v[2:5], off offset:1024
	s_nop 0
	ds_read_b128 v[18:21], v73
	ds_read_b128 v[22:25], v73 offset:1024
	ds_read_b128 v[26:29], v73 offset:2048
	ds_read_b128 v[30:33], v73 offset:3072
	ds_read_b128 v[38:41], v73 offset:4096
	ds_read_b128 v[42:45], v73 offset:5120
	ds_read_b128 v[34:37], v73 offset:6144
	ds_read_b128 v[46:49], v73 offset:7168
	ds_read_b128 v[232:235], v73 offset:8192
	ds_read_b128 v[236:239], v73 offset:9216
	ds_read_b128 v[50:53], v73 offset:10240
	ds_read_b128 v[54:57], v73 offset:11264
	s_waitcnt lgkmcnt(6)
	v_mul_f32_e32 v223, v96, v42
	v_fmac_f32_e32 v223, v94, v38
	v_mul_f32_e32 v1, v82, v22
	v_mul_f32_e32 v132, v83, v23
	v_fmac_f32_e32 v1, v78, v18
	v_mul_f32_e32 v133, v76, v24
	s_waitcnt lgkmcnt(2)
	v_mul_f32_e32 v135, v82, v236
	v_fmac_f32_e32 v132, v79, v19
	v_add_f32_e32 v1, 0, v1
	v_mul_f32_e32 v134, v77, v25
	v_mul_f32_e32 v136, v83, v237
	v_fmac_f32_e32 v133, v74, v20
	v_fmac_f32_e32 v135, v78, v232
	v_add_f32_e32 v1, v132, v1
	v_mul_f32_e32 v137, v76, v238
	v_fmac_f32_e32 v134, v75, v21
	v_fmac_f32_e32 v136, v79, v233
	v_add_f32_e32 v135, 0, v135
	v_add_f32_e32 v1, v133, v1
	v_mul_f32_e32 v133, v88, v30
	v_mul_f32_e32 v138, v77, v239
	v_fmac_f32_e32 v137, v74, v234
	v_add_f32_e32 v132, v136, v135
	v_add_f32_e32 v1, v134, v1
	v_mul_f32_e32 v134, v89, v31
	v_fmac_f32_e32 v133, v84, v26
	v_fmac_f32_e32 v138, v75, v235
	v_add_f32_e32 v132, v137, v132
	v_mul_f32_e32 v135, v86, v32
	s_waitcnt lgkmcnt(0)
	v_mul_f32_e32 v137, v88, v54
	v_fmac_f32_e32 v134, v85, v27
	v_add_f32_e32 v1, v133, v1
	v_add_f32_e32 v132, v138, v132
	v_mul_f32_e32 v136, v87, v33
	v_mul_f32_e32 v138, v89, v55
	v_fmac_f32_e32 v135, v80, v28
	v_fmac_f32_e32 v137, v84, v50
	v_add_f32_e32 v1, v134, v1
	v_fmac_f32_e32 v136, v81, v29
	v_fmac_f32_e32 v138, v85, v51
	v_add_f32_e32 v132, v137, v132
	v_add_f32_e32 v1, v135, v1
	v_add_f32_e32 v148, v138, v132
	v_add_f32_e32 v1, v136, v1
	v_add_f32_e32 v1, v223, v1
	s_waitcnt vmcnt(0)
	s_nop 1
	v_mov_b64_e32 v[10:11], v[150:151]
	v_mov_b64_e32 v[12:13], v[152:153]
	v_mov_b64_e32 v[14:15], v[154:155]
	v_mov_b64_e32 v[16:17], v[156:157]
	v_mov_b64_e32 v[6:7], v[158:159]
	v_mov_b64_e32 v[8:9], v[160:161]
	v_mov_b64_e32 v[2:3], v[162:163]
	v_mov_b64_e32 v[4:5], v[164:165]
	v_mov_b64_e32 v[224:225], v[166:167]
	v_mov_b64_e32 v[226:227], v[168:169]
	v_mov_b64_e32 v[228:229], v[170:171]
	v_mov_b64_e32 v[230:231], v[172:173]
	v_add_u32_e32 v150, 0x10400, v73
	v_add_u32_e32 v151, 0x10800, v73
	v_add_u32_e32 v152, 0x10c00, v73
	v_add_u32_e32 v153, 0x11000, v73
	v_add_u32_e32 v154, 0x11400, v73
	v_add_u32_e32 v155, 0x11800, v73
	v_add_u32_e32 v156, 0x11c00, v73
	v_add_u32_e32 v157, 0x12000, v73
	v_add_u32_e32 v158, 0x12400, v73
	v_add_u32_e32 v159, 0x12800, v73
	v_add_u32_e32 v160, 0x12c00, v73
	v_add_u32_e32 v161, 0x13000, v73
	v_add_u32_e32 v162, 0x13400, v73
	v_add_u32_e32 v163, 0x13800, v73
	v_add_u32_e32 v164, 0x13c00, v73
	v_add_u32_e32 v165, 0x14000, v73
	v_add_u32_e32 v166, 0x14400, v73
	v_add_u32_e32 v167, 0x14800, v73
	v_add_u32_e32 v168, 0x14c00, v73
	v_add_u32_e32 v169, 0x15000, v73
	v_add_u32_e32 v170, 0x15400, v73
	v_add_u32_e32 v171, 0x15800, v73
	v_add_u32_e32 v172, 0x15c00, v73
	v_add_u32_e32 v173, 0x16000, v73
	v_add_u32_e32 v174, 0x16400, v73
	v_add_u32_e32 v175, 0x16800, v73
	v_add_u32_e32 v176, 0x16c00, v73
	v_add_u32_e32 v177, 0x17000, v73
	v_add_u32_e32 v178, 0x17400, v73
	v_add_u32_e32 v179, 0x17800, v73
	v_add_u32_e32 v180, 0x17c00, v73
	v_add_u32_e32 v181, 0x18000, v73
	v_add_u32_e32 v182, 0x18400, v73
	v_add_u32_e32 v183, 0x18800, v73
	v_add_u32_e32 v184, 0x18c00, v73
	v_add_u32_e32 v185, 0x19000, v73
	v_add_u32_e32 v186, 0x19400, v73
	v_add_u32_e32 v187, 0x19800, v73
	v_add_u32_e32 v188, 0x19c00, v73
	v_add_u32_e32 v189, 0x1a000, v73
	v_add_u32_e32 v190, 0x1a400, v73
	v_add_u32_e32 v191, 0x1a800, v73
	v_add_u32_e32 v192, 0x1ac00, v73
	v_add_u32_e32 v193, 0x1b000, v73
; #define LAS __attribute__((address_space(3)))
; __device__ __forceinline__ unsigned pk2(float lo, float hi) { return f2bf(lo) | (f2bf(hi) << 16); }
; template <bool ZP, bool XF32, bool OUT8 = false>
; __device__ __forceinline__ void norm_phase(LAS unsigned char* lds, const void* xin, const float* gain, const float* sh, const float* sc, bf16* hout, const float* wzt, float* zout, int lane, int wave, int vcu, int G) {
;     ...
;             for (int j = 0; j < 4; ++j) { const int col = 512 * j + 8 * lane;
; #pragma unroll
;                 for (int q = 0; q < 2; ++q) { const f32x4 gg = *(const f32x4*)(gain + col + 4 * q), s1 = *(const f32x4*)(sc + (size_t)b * MODW + col + 4 * q), s0 = *(const f32x4*)(sh + (size_t)b * MODW + col + 4 * q);
;                     v[r][j][q] = (v[r][j][q] * rstd * gg) * (s1 + 1.0f) + s0; }
;                 if constexpr (OUT8) { *(v2u*)((unsigned char*)hout + (size_t)m * D + col) = pack8_fp8(v[r][j][0][0], v[r][j][0][1], v[r][j][0][2], v[r][j][0][3], v[r][j][1][0], v[r][j][1][1], v[r][j][1][2], v[r][j][1][3], FP8_ASCALE); }
;                 else { v4u o; o.x = pk2(v[r][j][0][0], v[r][j][0][1]); o.y = pk2(v[r][j][0][2], v[r][j][0][3]); o.z = pk2(v[r][j][1][0], v[r][j][1][1]); o.w = pk2(v[r][j][1][2], v[r][j][1][3]);
;                     *(v4u*)(hout + (size_t)m * D + col) = o; } }
;         }
;         if constexpr (ZP) {
;             float p0[16], p1[16];
; #pragma unroll
;             for (int rr = 0; rr < 16; ++rr) { p0[rr] = 0.f; p1[rr] = 0.f;
; #pragma unroll
;                 for (int j = 0; j < 4; ++j) { const f32x4 w0 = *(const LAS f32x4*)(wl + (((rr * 4 + j) * 2 + 0) * 64 + lane) * 4), w1 = *(const LAS f32x4*)(wl + (((rr * 4 + j) * 2 + 1) * 64 + lane) * 4);
; #pragma unroll
;                     for (int e = 0; e < 4; ++e) { p0[rr] += v[0][j][0][e] * w0[e] + v[0][j][1][e] * w1[e]; p1[rr] += v[1][j][0][e] * w0[e] + v[1][j][1][e] * w1[e]; } } }
	v_add_u32_e32 v194, 0x1b400, v73
	v_add_u32_e32 v195, 0x1b800, v73
	v_add_u32_e32 v196, 0x1bc00, v73
	v_add_u32_e32 v197, 0x1c000, v73
	v_pk_mul_f32 v[10:11], v[124:125], v[10:11]
	v_pk_mul_f32 v[12:13], v[126:127], v[12:13]
	v_pk_add_f32 v[16:17], v[16:17], 1.0 op_sel_hi:[1,0]
	v_pk_add_f32 v[14:15], v[14:15], 1.0 op_sel_hi:[1,0]
	v_pk_mul_f32 v[6:7], v[130:131], v[6:7]
	v_pk_mul_f32 v[124:125], v[128:129], v[8:9]
	v_pk_add_f32 v[4:5], v[4:5], 1.0 op_sel_hi:[1,0]
	v_pk_add_f32 v[2:3], v[2:3], 1.0 op_sel_hi:[1,0]
	v_pk_fma_f32 v[8:9], v[12:13], v[16:17], v[230:231]
	v_pk_fma_f32 v[12:13], v[10:11], v[14:15], v[228:229]
	v_pk_fma_f32 v[10:11], v[124:125], v[4:5], v[226:227]
	v_pk_fma_f32 v[14:15], v[6:7], v[2:3], v[224:225]
	v_bfe_u32 v2, v12, 16, 1
	v_bfe_u32 v4, v8, 16, 1
	v_bfe_u32 v6, v14, 16, 1
	v_bfe_u32 v16, v10, 16, 1
	v_bfe_u32 v3, v13, 16, 1
	v_bfe_u32 v5, v9, 16, 1
	v_bfe_u32 v7, v15, 16, 1
	v_bfe_u32 v17, v11, 16, 1
	v_add3_u32 v2, v12, v2, s41
	v_add3_u32 v4, v8, v4, s41
	v_add3_u32 v6, v14, v6, s41
	v_add3_u32 v16, v10, v16, s41
	v_add3_u32 v3, v13, v3, s41
	v_add3_u32 v5, v9, v5, s41
	v_add3_u32 v7, v15, v7, s41
	v_add3_u32 v17, v11, v17, s41
	v_lshrrev_b32_e32 v2, 16, v2
	v_lshrrev_b32_e32 v4, 16, v4
	v_lshrrev_b32_e32 v6, 16, v6
	v_lshrrev_b32_e32 v16, 16, v16
	v_and_or_b32 v2, v3, s39, v2
	v_and_or_b32 v3, v5, s39, v4
	v_and_or_b32 v4, v7, s39, v6
	v_and_or_b32 v5, v17, s39, v16
	global_store_dwordx4 v[98:99], v[2:5], off offset:2048
	global_load_dwordx4 v[124:127], v[68:69], off offset:16
	global_load_dwordx4 v[128:131], v[68:69], off
	global_load_dwordx4 v[132:135], v215, s[24:25] offset:16
	global_load_dwordx4 v[136:139], v215, s[24:25]
	global_load_dwordx4 v[140:143], v215, s[26:27] offset:16
	global_load_dwordx4 v[144:147], v215, s[26:27]
	v_mul_f32_e32 v2, v97, v43
	v_mul_f32_e32 v3, v92, v44
	v_fmac_f32_e32 v2, v95, v39
	v_mul_f32_e32 v4, v93, v45
	v_fmac_f32_e32 v3, v90, v40
	v_add_f32_e32 v1, v2, v1
	v_fmac_f32_e32 v4, v91, v41
	v_add_f32_e32 v1, v3, v1
	v_mul_f32_e32 v2, v106, v46
	v_add_f32_e32 v1, v4, v1
	v_mul_f32_e32 v3, v107, v47
	v_fmac_f32_e32 v2, v104, v34
	v_mul_f32_e32 v4, v102, v48
	v_fmac_f32_e32 v3, v105, v35
	v_add_f32_e32 v1, v2, v1
	v_mul_f32_e32 v5, v103, v49
	v_fmac_f32_e32 v4, v100, v36
	v_add_f32_e32 v1, v3, v1
	v_fmac_f32_e32 v5, v101, v37
	v_add_f32_e32 v1, v4, v1
	v_add_f32_e32 v5, v5, v1
	v_mul_f32_e32 v1, v114, v22
	v_mul_f32_e32 v2, v115, v23
	v_fmac_f32_e32 v1, v112, v18
	v_mul_f32_e32 v3, v110, v24
	v_mul_f32_e32 v6, v114, v236
	v_fmac_f32_e32 v2, v113, v19
	v_add_f32_e32 v1, 0, v1
	v_mul_f32_e32 v4, v111, v25
	v_mul_f32_e32 v7, v115, v237
	v_fmac_f32_e32 v3, v108, v20
	v_fmac_f32_e32 v6, v112, v232
	v_add_f32_e32 v1, v2, v1
	v_mul_f32_e32 v16, v110, v238
	v_fmac_f32_e32 v4, v109, v21
	v_fmac_f32_e32 v7, v113, v233
	v_add_f32_e32 v6, 0, v6
	v_add_f32_e32 v1, v3, v1
	v_mul_f32_e32 v3, v122, v30
	v_mul_f32_e32 v17, v111, v239
	v_fmac_f32_e32 v16, v108, v234
	v_add_f32_e32 v2, v7, v6
	v_add_f32_e32 v1, v4, v1
	v_mul_f32_e32 v4, v123, v31
	v_fmac_f32_e32 v3, v120, v26
	v_fmac_f32_e32 v17, v109, v235
	v_add_f32_e32 v2, v16, v2
	v_mul_f32_e32 v6, v118, v32
	v_mul_f32_e32 v16, v122, v54
	v_fmac_f32_e32 v4, v121, v27
	v_add_f32_e32 v1, v3, v1
	v_add_f32_e32 v2, v17, v2
	v_mul_f32_e32 v7, v119, v33
	v_fmac_f32_e32 v6, v116, v28
	v_fmac_f32_e32 v16, v120, v50
	v_add_f32_e32 v1, v4, v1
	v_fmac_f32_e32 v7, v117, v29
	v_add_f32_e32 v28, v16, v2
	v_add_f32_e32 v1, v6, v1
	v_mul_f32_e32 v2, v14, v42
	v_add_f32_e32 v1, v7, v1
	v_mul_f32_e32 v3, v15, v43
	v_fmac_f32_e32 v2, v12, v38
	v_mul_f32_e32 v4, v10, v44
	v_fmac_f32_e32 v3, v13, v39
	v_add_f32_e32 v1, v2, v1
	v_mul_f32_e32 v6, v11, v45
	v_fmac_f32_e32 v4, v8, v40
	v_add_f32_e32 v1, v3, v1
	v_fmac_f32_e32 v6, v9, v41
	v_add_f32_e32 v1, v4, v1
	v_add_f32_e32 v4, v6, v1
	v_mul_f32_e32 v30, v123, v55
	v_fmac_f32_e32 v30, v121, v51
	v_mul_f32_e32 v33, v87, v57
	s_waitcnt vmcnt(5)
	v_pk_mul_f32 v[20:21], v[246:247], v[124:125]
	s_waitcnt vmcnt(4)
	v_pk_mul_f32 v[6:7], v[240:241], v[130:131]
	s_waitcnt vmcnt(3)
	v_pk_add_f32 v[26:27], v[132:133], 1.0 op_sel_hi:[1,0]
	s_waitcnt vmcnt(2)
	v_pk_add_f32 v[16:17], v[138:139], 1.0 op_sel_hi:[1,0]
	v_pk_mul_f32 v[22:23], v[244:245], v[126:127]
	v_pk_add_f32 v[24:25], v[134:135], 1.0 op_sel_hi:[1,0]
	s_waitcnt vmcnt(1)
	v_pk_fma_f32 v[20:21], v[20:21], v[26:27], v[140:141]
	v_pk_mul_f32 v[2:3], v[242:243], v[128:129]
	v_pk_add_f32 v[18:19], v[136:137], 1.0 op_sel_hi:[1,0]
	s_waitcnt vmcnt(0)
	v_pk_fma_f32 v[16:17], v[6:7], v[16:17], v[146:147]
	v_pk_fma_f32 v[6:7], v[22:23], v[24:25], v[142:143]
	v_bfe_u32 v24, v20, 16, 1
	v_pk_fma_f32 v[18:19], v[2:3], v[18:19], v[144:145]
	v_bfe_u32 v25, v21, 16, 1
	v_mul_f32_e32 v26, v20, v46
	v_add3_u32 v24, v20, v24, s41
	v_bfe_u32 v2, v18, 16, 1
	v_bfe_u32 v22, v16, 16, 1
	v_add3_u32 v25, v21, v25, s41
	v_fmac_f32_e32 v26, v18, v34
	v_lshrrev_b32_e32 v24, 16, v24
	v_bfe_u32 v3, v19, 16, 1
	v_bfe_u32 v23, v17, 16, 1
	v_mul_f32_e32 v27, v21, v47
	v_add3_u32 v2, v18, v2, s41
	v_add3_u32 v22, v16, v22, s41
	v_add_f32_e32 v26, v26, v4
	v_and_or_b32 v4, v25, s39, v24
	v_mul_f32_e32 v24, v86, v56
	v_mul_f32_e32 v29, v6, v48
	v_add3_u32 v3, v19, v3, s41
	v_add3_u32 v23, v17, v23, s41
	v_fmac_f32_e32 v27, v19, v35
	v_lshrrev_b32_e32 v2, 16, v2
	v_lshrrev_b32_e32 v22, 16, v22
	v_fmac_f32_e32 v24, v80, v52
	v_mul_f32_e32 v31, v7, v49
	v_fmac_f32_e32 v29, v16, v36
	v_and_or_b32 v2, v3, s39, v2
	v_and_or_b32 v3, v23, s39, v22
	v_add_f32_e32 v22, v27, v26
	v_add_f32_e32 v32, v24, v148
	v_mul_f32_e32 v24, v118, v56
	v_fmac_f32_e32 v31, v17, v37
	v_add_f32_e32 v22, v29, v22
	v_add_f32_e32 v23, v30, v28
	v_fmac_f32_e32 v24, v116, v52
	v_add_f32_e32 v22, v31, v22
	v_add_f32_e32 v23, v24, v23
	ds_read_b128 v[24:27], v73 offset:12288
	ds_read_b128 v[28:31], v73 offset:13312
	v_fmac_f32_e32 v33, v81, v53
	v_add_f32_e32 v32, v33, v32
	v_mul_f32_e32 v33, v119, v57
	v_fmac_f32_e32 v33, v117, v53
	v_add_f32_e32 v23, v33, v23
	s_waitcnt lgkmcnt(0)
; #define LAS __attribute__((address_space(3)))
; template <bool ZP, bool XF32, bool OUT8 = false>
; __device__ __forceinline__ void norm_phase(LAS unsigned char* lds, const void* xin, const float* gain, const float* sh, const float* sc, bf16* hout, const float* wzt, float* zout, int lane, int wave, int vcu, int G) {
;     ...
;         if constexpr (ZP) {
;             float p0[16], p1[16];
; #pragma unroll
;             for (int rr = 0; rr < 16; ++rr) { p0[rr] = 0.f; p1[rr] = 0.f;
; #pragma unroll
;                 for (int j = 0; j < 4; ++j) { const f32x4 w0 = *(const LAS f32x4*)(wl + (((rr * 4 + j) * 2 + 0) * 64 + lane) * 4), w1 = *(const LAS f32x4*)(wl + (((rr * 4 + j) * 2 + 1) * 64 + lane) * 4);
; #pragma unroll
;                     for (int e = 0; e < 4; ++e) { p0[rr] += v[0][j][0][e] * w0[e] + v[0][j][1][e] * w1[e]; p1[rr] += v[1][j][0][e] * w0[e] + v[1][j][1][e] * w1[e]; } } }
	v_mul_f32_e32 v33, v96, v28
	v_mul_f32_e32 v28, v14, v28
	v_fmac_f32_e32 v28, v12, v24
	v_fmac_f32_e32 v33, v94, v24
	v_add_f32_e32 v23, v28, v23
	v_mul_f32_e32 v24, v97, v29
	v_mul_f32_e32 v28, v15, v29
	v_add_f32_e32 v32, v33, v32
	v_fmac_f32_e32 v24, v95, v25
	v_fmac_f32_e32 v28, v13, v25
	v_mul_f32_e32 v25, v92, v30
	v_add_f32_e32 v24, v24, v32
	v_fmac_f32_e32 v25, v90, v26
	v_add_f32_e32 v24, v25, v24
	v_mul_f32_e32 v25, v10, v30
	v_add_f32_e32 v23, v28, v23
	v_fmac_f32_e32 v25, v8, v26
	ds_read_b128 v[32:35], v73 offset:14336
	ds_read_b128 v[36:39], v73 offset:15360
	v_add_f32_e32 v23, v25, v23
	v_mul_f32_e32 v25, v93, v31
	v_fmac_f32_e32 v25, v91, v27
	v_add_f32_e32 v24, v25, v24
	v_mul_f32_e32 v25, v11, v31
	v_fmac_f32_e32 v25, v9, v27
	v_add_f32_e32 v23, v25, v23
	s_waitcnt lgkmcnt(0)
	v_mul_f32_e32 v25, v106, v36
	v_fmac_f32_e32 v25, v104, v32
	v_add_f32_e32 v24, v25, v24
	v_mul_f32_e32 v25, v20, v36
	v_fmac_f32_e32 v25, v18, v32
	v_add_f32_e32 v23, v25, v23
	v_mul_f32_e32 v25, v107, v37
	v_fmac_f32_e32 v25, v105, v33
	v_add_f32_e32 v24, v25, v24
	v_mul_f32_e32 v25, v21, v37
	v_fmac_f32_e32 v25, v19, v33
	v_add_f32_e32 v23, v25, v23
	v_mul_f32_e32 v25, v102, v38
	v_fmac_f32_e32 v25, v100, v34
	v_add_f32_e32 v24, v25, v24
	v_mul_f32_e32 v25, v6, v38
	v_fmac_f32_e32 v25, v16, v34
	ds_read_b128 v[26:29], v73 offset:16384
	ds_read_b128 v[30:33], v73 offset:17408
	v_add_f32_e32 v23, v25, v23
	v_mul_f32_e32 v25, v103, v39
	v_fmac_f32_e32 v25, v101, v35
	v_add_f32_e32 v24, v25, v24
	v_mul_f32_e32 v25, v7, v39
	v_fmac_f32_e32 v25, v17, v35
	v_add_f32_e32 v23, v25, v23
	s_waitcnt lgkmcnt(0)
	v_mul_f32_e32 v25, v82, v30
	v_mul_f32_e32 v30, v114, v30
	v_fmac_f32_e32 v30, v112, v26
	v_fmac_f32_e32 v25, v78, v26
	v_add_f32_e32 v26, 0, v30
	v_mul_f32_e32 v30, v83, v31
	v_add_f32_e32 v25, 0, v25
	v_fmac_f32_e32 v30, v79, v27
	v_add_f32_e32 v25, v30, v25
	v_mul_f32_e32 v30, v115, v31
	v_fmac_f32_e32 v30, v113, v27
	v_mul_f32_e32 v27, v76, v32
	v_fmac_f32_e32 v27, v74, v28
	v_add_f32_e32 v25, v27, v25
	v_mul_f32_e32 v27, v110, v32
	v_add_f32_e32 v26, v30, v26
	v_fmac_f32_e32 v27, v108, v28
	ds_read_b128 v[34:37], v73 offset:18432
	ds_read_b128 v[38:41], v73 offset:19456
	v_add_f32_e32 v26, v27, v26
	v_mul_f32_e32 v27, v77, v33
	v_fmac_f32_e32 v27, v75, v29
	v_add_f32_e32 v25, v27, v25
	v_mul_f32_e32 v27, v111, v33
	v_fmac_f32_e32 v27, v109, v29
	v_add_f32_e32 v26, v27, v26
	s_waitcnt lgkmcnt(0)
	v_mul_f32_e32 v27, v88, v38
	v_fmac_f32_e32 v27, v84, v34
	v_add_f32_e32 v25, v27, v25
	v_mul_f32_e32 v27, v122, v38
	v_fmac_f32_e32 v27, v120, v34
	v_add_f32_e32 v26, v27, v26
	v_mul_f32_e32 v27, v89, v39
	v_fmac_f32_e32 v27, v85, v35
	v_add_f32_e32 v25, v27, v25
	v_mul_f32_e32 v27, v123, v39
	v_fmac_f32_e32 v27, v121, v35
	v_add_f32_e32 v26, v27, v26
	v_mul_f32_e32 v27, v86, v40
	v_fmac_f32_e32 v27, v80, v36
	v_add_f32_e32 v25, v27, v25
	v_mul_f32_e32 v27, v118, v40
	v_fmac_f32_e32 v27, v116, v36
	v_add_f32_e32 v34, v27, v26
	ds_read_b128 v[26:29], v73 offset:20480
	ds_read_b128 v[30:33], v73 offset:21504
	v_mul_f32_e32 v35, v87, v41
	v_fmac_f32_e32 v35, v81, v37
	v_add_f32_e32 v25, v35, v25
	v_mul_f32_e32 v35, v119, v41
	v_fmac_f32_e32 v35, v117, v37
	v_add_f32_e32 v34, v35, v34
	s_waitcnt lgkmcnt(0)
	v_mul_f32_e32 v35, v96, v30
	v_mul_f32_e32 v30, v14, v30
	v_fmac_f32_e32 v30, v12, v26
	v_fmac_f32_e32 v35, v94, v26
	v_add_f32_e32 v26, v30, v34
	v_mul_f32_e32 v30, v97, v31
	v_add_f32_e32 v25, v35, v25
	v_fmac_f32_e32 v30, v95, v27
	v_add_f32_e32 v25, v30, v25
	v_mul_f32_e32 v30, v15, v31
	v_fmac_f32_e32 v30, v13, v27
	v_mul_f32_e32 v27, v92, v32
	v_fmac_f32_e32 v27, v90, v28
	v_add_f32_e32 v25, v27, v25
	v_mul_f32_e32 v27, v10, v32
	v_add_f32_e32 v26, v30, v26
	v_fmac_f32_e32 v27, v8, v28
	ds_read_b128 v[34:37], v73 offset:22528
	ds_read_b128 v[38:41], v73 offset:23552
	v_add_f32_e32 v26, v27, v26
	v_mul_f32_e32 v27, v93, v33
	v_fmac_f32_e32 v27, v91, v29
	v_add_f32_e32 v25, v27, v25
	v_mul_f32_e32 v27, v11, v33
	v_fmac_f32_e32 v27, v9, v29
	v_add_f32_e32 v26, v27, v26
	s_waitcnt lgkmcnt(0)
	v_mul_f32_e32 v27, v106, v38
	v_fmac_f32_e32 v27, v104, v34
	v_add_f32_e32 v25, v27, v25
	v_mul_f32_e32 v27, v20, v38
	v_fmac_f32_e32 v27, v18, v34
	v_add_f32_e32 v26, v27, v26
	v_mul_f32_e32 v27, v107, v39
	v_fmac_f32_e32 v27, v105, v35
	v_add_f32_e32 v25, v27, v25
	v_mul_f32_e32 v27, v21, v39
	v_fmac_f32_e32 v27, v19, v35
	v_add_f32_e32 v26, v27, v26
	v_mul_f32_e32 v27, v102, v40
	v_fmac_f32_e32 v27, v100, v36
	v_add_f32_e32 v25, v27, v25
	v_mul_f32_e32 v27, v6, v40
	v_fmac_f32_e32 v27, v16, v36
	ds_read_b128 v[28:31], v73 offset:24576
	ds_read_b128 v[32:35], v73 offset:25600
	v_add_f32_e32 v27, v27, v26
	v_mul_f32_e32 v26, v103, v41
	v_fmac_f32_e32 v26, v101, v37
	v_add_f32_e32 v26, v26, v25
	v_mul_f32_e32 v25, v7, v41
	v_fmac_f32_e32 v25, v17, v37
	v_add_f32_e32 v25, v25, v27
	s_waitcnt lgkmcnt(0)
	v_mul_f32_e32 v27, v82, v32
	v_mul_f32_e32 v32, v114, v32
	v_fmac_f32_e32 v32, v112, v28
	v_fmac_f32_e32 v27, v78, v28
	v_add_f32_e32 v28, 0, v32
	v_mul_f32_e32 v32, v83, v33
	v_add_f32_e32 v27, 0, v27
	v_fmac_f32_e32 v32, v79, v29
	v_add_f32_e32 v27, v32, v27
	v_mul_f32_e32 v32, v115, v33
	v_fmac_f32_e32 v32, v113, v29
	v_mul_f32_e32 v29, v76, v34
	v_fmac_f32_e32 v29, v74, v30
	v_add_f32_e32 v27, v29, v27
	v_mul_f32_e32 v29, v110, v34
	v_add_f32_e32 v28, v32, v28
	v_fmac_f32_e32 v29, v108, v30
	ds_read_b128 v[36:39], v73 offset:26624
	ds_read_b128 v[40:43], v73 offset:27648
	v_add_f32_e32 v28, v29, v28
	v_mul_f32_e32 v29, v77, v35
	v_fmac_f32_e32 v29, v75, v31
	v_add_f32_e32 v27, v29, v27
	v_mul_f32_e32 v29, v111, v35
	v_fmac_f32_e32 v29, v109, v31
	v_add_f32_e32 v28, v29, v28
	s_waitcnt lgkmcnt(0)
; #define LAS __attribute__((address_space(3)))
; template <bool ZP, bool XF32, bool OUT8 = false>
; __device__ __forceinline__ void norm_phase(LAS unsigned char* lds, const void* xin, const float* gain, const float* sh, const float* sc, bf16* hout, const float* wzt, float* zout, int lane, int wave, int vcu, int G) {
;     ...
;         if constexpr (ZP) {
;             float p0[16], p1[16];
; #pragma unroll
;             for (int rr = 0; rr < 16; ++rr) { p0[rr] = 0.f; p1[rr] = 0.f;
; #pragma unroll
;                 for (int j = 0; j < 4; ++j) { const f32x4 w0 = *(const LAS f32x4*)(wl + (((rr * 4 + j) * 2 + 0) * 64 + lane) * 4), w1 = *(const LAS f32x4*)(wl + (((rr * 4 + j) * 2 + 1) * 64 + lane) * 4);
; #pragma unroll
;                     for (int e = 0; e < 4; ++e) { p0[rr] += v[0][j][0][e] * w0[e] + v[0][j][1][e] * w1[e]; p1[rr] += v[1][j][0][e] * w0[e] + v[1][j][1][e] * w1[e]; } } }
	v_mul_f32_e32 v29, v88, v40
	v_fmac_f32_e32 v29, v84, v36
	v_add_f32_e32 v27, v29, v27
	v_mul_f32_e32 v29, v122, v40
	v_fmac_f32_e32 v29, v120, v36
	v_add_f32_e32 v28, v29, v28
	v_mul_f32_e32 v29, v89, v41
	v_fmac_f32_e32 v29, v85, v37
	v_add_f32_e32 v27, v29, v27
	v_mul_f32_e32 v29, v123, v41
	v_fmac_f32_e32 v29, v121, v37
	v_add_f32_e32 v28, v29, v28
	v_mul_f32_e32 v29, v86, v42
	v_fmac_f32_e32 v29, v80, v38
	v_add_f32_e32 v27, v29, v27
	v_mul_f32_e32 v29, v118, v42
	v_fmac_f32_e32 v29, v116, v38
	v_add_f32_e32 v36, v29, v28
	ds_read_b128 v[28:31], v73 offset:28672
	ds_read_b128 v[32:35], v73 offset:29696
	v_mul_f32_e32 v37, v87, v43
	v_fmac_f32_e32 v37, v81, v39
	v_add_f32_e32 v27, v37, v27
	v_mul_f32_e32 v37, v119, v43
	v_fmac_f32_e32 v37, v117, v39
	v_add_f32_e32 v36, v37, v36
	s_waitcnt lgkmcnt(0)
	v_mul_f32_e32 v37, v96, v32
	v_mul_f32_e32 v32, v14, v32
	v_fmac_f32_e32 v32, v12, v28
	v_fmac_f32_e32 v37, v94, v28
	v_add_f32_e32 v28, v32, v36
	v_mul_f32_e32 v32, v97, v33
	v_add_f32_e32 v27, v37, v27
	v_fmac_f32_e32 v32, v95, v29
	v_add_f32_e32 v27, v32, v27
	v_mul_f32_e32 v32, v15, v33
	v_fmac_f32_e32 v32, v13, v29
	v_mul_f32_e32 v29, v92, v34
	v_fmac_f32_e32 v29, v90, v30
	v_add_f32_e32 v27, v29, v27
	v_mul_f32_e32 v29, v10, v34
	v_add_f32_e32 v28, v32, v28
	v_fmac_f32_e32 v29, v8, v30
	ds_read_b128 v[36:39], v73 offset:30720
	ds_read_b128 v[40:43], v73 offset:31744
	v_add_f32_e32 v28, v29, v28
	v_mul_f32_e32 v29, v93, v35
	v_fmac_f32_e32 v29, v91, v31
	v_add_f32_e32 v27, v29, v27
	v_mul_f32_e32 v29, v11, v35
	v_fmac_f32_e32 v29, v9, v31
	v_add_f32_e32 v28, v29, v28
	s_waitcnt lgkmcnt(0)
	v_mul_f32_e32 v29, v106, v40
	v_fmac_f32_e32 v29, v104, v36
	v_add_f32_e32 v27, v29, v27
	v_mul_f32_e32 v29, v20, v40
	v_fmac_f32_e32 v29, v18, v36
	v_add_f32_e32 v28, v29, v28
	v_mul_f32_e32 v29, v107, v41
	v_fmac_f32_e32 v29, v105, v37
	v_add_f32_e32 v27, v29, v27
	v_mul_f32_e32 v29, v21, v41
	v_fmac_f32_e32 v29, v19, v37
	v_add_f32_e32 v28, v29, v28
	v_mul_f32_e32 v29, v102, v42
	v_fmac_f32_e32 v29, v100, v38
	v_add_f32_e32 v27, v29, v27
	v_mul_f32_e32 v29, v6, v42
	v_fmac_f32_e32 v29, v16, v38
	ds_read_b128 v[30:33], v73 offset:32768
	ds_read_b128 v[34:37], v73 offset:33792
	v_add_f32_e32 v29, v29, v28
	v_mul_f32_e32 v28, v103, v43
	v_fmac_f32_e32 v28, v101, v39
	v_add_f32_e32 v28, v28, v27
	v_mul_f32_e32 v27, v7, v43
	v_fmac_f32_e32 v27, v17, v39
	v_add_f32_e32 v27, v27, v29
	s_waitcnt lgkmcnt(0)
	v_mul_f32_e32 v29, v82, v34
	v_mul_f32_e32 v34, v114, v34
	v_fmac_f32_e32 v34, v112, v30
	v_fmac_f32_e32 v29, v78, v30
	v_add_f32_e32 v30, 0, v34
	v_mul_f32_e32 v34, v83, v35
	v_add_f32_e32 v29, 0, v29
	v_fmac_f32_e32 v34, v79, v31
	v_add_f32_e32 v29, v34, v29
	v_mul_f32_e32 v34, v115, v35
	v_fmac_f32_e32 v34, v113, v31
	v_mul_f32_e32 v31, v76, v36
	v_fmac_f32_e32 v31, v74, v32
	v_add_f32_e32 v29, v31, v29
	v_mul_f32_e32 v31, v110, v36
	v_add_f32_e32 v30, v34, v30
	v_fmac_f32_e32 v31, v108, v32
	ds_read_b128 v[38:41], v73 offset:34816
	ds_read_b128 v[42:45], v73 offset:35840
	v_add_f32_e32 v30, v31, v30
	v_mul_f32_e32 v31, v77, v37
	v_fmac_f32_e32 v31, v75, v33
	v_add_f32_e32 v29, v31, v29
	v_mul_f32_e32 v31, v111, v37
	v_fmac_f32_e32 v31, v109, v33
	v_add_f32_e32 v30, v31, v30
	s_waitcnt lgkmcnt(0)
	v_mul_f32_e32 v31, v88, v42
	v_fmac_f32_e32 v31, v84, v38
	v_add_f32_e32 v29, v31, v29
	v_mul_f32_e32 v31, v122, v42
	v_fmac_f32_e32 v31, v120, v38
	v_add_f32_e32 v30, v31, v30
	v_mul_f32_e32 v31, v89, v43
	v_fmac_f32_e32 v31, v85, v39
	v_add_f32_e32 v29, v31, v29
	v_mul_f32_e32 v31, v123, v43
	v_fmac_f32_e32 v31, v121, v39
	v_add_f32_e32 v30, v31, v30
	v_mul_f32_e32 v31, v86, v44
	v_fmac_f32_e32 v31, v80, v40
	v_add_f32_e32 v29, v31, v29
	v_mul_f32_e32 v31, v118, v44
	v_fmac_f32_e32 v31, v116, v40
	v_add_f32_e32 v38, v31, v30
	ds_read_b128 v[30:33], v73 offset:36864
	ds_read_b128 v[34:37], v73 offset:37888
	v_mul_f32_e32 v39, v87, v45
	v_fmac_f32_e32 v39, v81, v41
	v_add_f32_e32 v29, v39, v29
	v_mul_f32_e32 v39, v119, v45
	v_fmac_f32_e32 v39, v117, v41
	v_add_f32_e32 v38, v39, v38
	s_waitcnt lgkmcnt(0)
	v_mul_f32_e32 v39, v96, v34
	v_mul_f32_e32 v34, v14, v34
	v_fmac_f32_e32 v34, v12, v30
	v_fmac_f32_e32 v39, v94, v30
	v_add_f32_e32 v30, v34, v38
	v_mul_f32_e32 v34, v97, v35
	v_add_f32_e32 v29, v39, v29
	v_fmac_f32_e32 v34, v95, v31
	v_add_f32_e32 v29, v34, v29
	v_mul_f32_e32 v34, v15, v35
	v_fmac_f32_e32 v34, v13, v31
	v_mul_f32_e32 v31, v92, v36
	v_fmac_f32_e32 v31, v90, v32
	v_add_f32_e32 v29, v31, v29
	v_mul_f32_e32 v31, v10, v36
	v_add_f32_e32 v30, v34, v30
	v_fmac_f32_e32 v31, v8, v32
	ds_read_b128 v[38:41], v73 offset:38912
	ds_read_b128 v[42:45], v73 offset:39936
	v_add_f32_e32 v30, v31, v30
	v_mul_f32_e32 v31, v93, v37
	v_fmac_f32_e32 v31, v91, v33
	v_add_f32_e32 v29, v31, v29
	v_mul_f32_e32 v31, v11, v37
	v_fmac_f32_e32 v31, v9, v33
	v_add_f32_e32 v30, v31, v30
	s_waitcnt lgkmcnt(0)
	v_mul_f32_e32 v31, v106, v42
	v_fmac_f32_e32 v31, v104, v38
	v_add_f32_e32 v29, v31, v29
	v_mul_f32_e32 v31, v20, v42
	v_fmac_f32_e32 v31, v18, v38
	v_add_f32_e32 v30, v31, v30
	v_mul_f32_e32 v31, v107, v43
	v_fmac_f32_e32 v31, v105, v39
	v_add_f32_e32 v29, v31, v29
	v_mul_f32_e32 v31, v21, v43
	v_fmac_f32_e32 v31, v19, v39
	v_add_f32_e32 v30, v31, v30
	v_mul_f32_e32 v31, v102, v44
	v_fmac_f32_e32 v31, v100, v40
	v_add_f32_e32 v29, v31, v29
	v_mul_f32_e32 v31, v6, v44
	v_fmac_f32_e32 v31, v16, v40
	ds_read_b128 v[32:35], v73 offset:40960
	ds_read_b128 v[36:39], v73 offset:41984
	v_add_f32_e32 v31, v31, v30
	v_mul_f32_e32 v30, v103, v45
	v_fmac_f32_e32 v30, v101, v41
	v_add_f32_e32 v30, v30, v29
	v_mul_f32_e32 v29, v7, v45
	v_fmac_f32_e32 v29, v17, v41
	v_add_f32_e32 v29, v29, v31
	s_waitcnt lgkmcnt(0)
; #define LAS __attribute__((address_space(3)))
; template <bool ZP, bool XF32, bool OUT8 = false>
; __device__ __forceinline__ void norm_phase(LAS unsigned char* lds, const void* xin, const float* gain, const float* sh, const float* sc, bf16* hout, const float* wzt, float* zout, int lane, int wave, int vcu, int G) {
;     ...
;         if constexpr (ZP) {
;             float p0[16], p1[16];
; #pragma unroll
;             for (int rr = 0; rr < 16; ++rr) { p0[rr] = 0.f; p1[rr] = 0.f;
; #pragma unroll
;                 for (int j = 0; j < 4; ++j) { const f32x4 w0 = *(const LAS f32x4*)(wl + (((rr * 4 + j) * 2 + 0) * 64 + lane) * 4), w1 = *(const LAS f32x4*)(wl + (((rr * 4 + j) * 2 + 1) * 64 + lane) * 4);
; #pragma unroll
;                     for (int e = 0; e < 4; ++e) { p0[rr] += v[0][j][0][e] * w0[e] + v[0][j][1][e] * w1[e]; p1[rr] += v[1][j][0][e] * w0[e] + v[1][j][1][e] * w1[e]; } } }
	v_mul_f32_e32 v31, v82, v36
	v_mul_f32_e32 v36, v114, v36
	v_fmac_f32_e32 v36, v112, v32
	v_fmac_f32_e32 v31, v78, v32
	v_add_f32_e32 v32, 0, v36
	v_mul_f32_e32 v36, v83, v37
	v_add_f32_e32 v31, 0, v31
	v_fmac_f32_e32 v36, v79, v33
	v_add_f32_e32 v31, v36, v31
	v_mul_f32_e32 v36, v115, v37
	v_fmac_f32_e32 v36, v113, v33
	v_mul_f32_e32 v33, v76, v38
	v_fmac_f32_e32 v33, v74, v34
	v_add_f32_e32 v31, v33, v31
	v_mul_f32_e32 v33, v110, v38
	v_add_f32_e32 v32, v36, v32
	v_fmac_f32_e32 v33, v108, v34
	ds_read_b128 v[40:43], v73 offset:43008
	ds_read_b128 v[44:47], v73 offset:44032
	v_add_f32_e32 v32, v33, v32
	v_mul_f32_e32 v33, v77, v39
	v_fmac_f32_e32 v33, v75, v35
	v_add_f32_e32 v31, v33, v31
	v_mul_f32_e32 v33, v111, v39
	v_fmac_f32_e32 v33, v109, v35
	v_add_f32_e32 v32, v33, v32
	s_waitcnt lgkmcnt(0)
	v_mul_f32_e32 v33, v88, v44
	v_fmac_f32_e32 v33, v84, v40
	v_add_f32_e32 v31, v33, v31
	v_mul_f32_e32 v33, v122, v44
	v_fmac_f32_e32 v33, v120, v40
	v_add_f32_e32 v32, v33, v32
	v_mul_f32_e32 v33, v89, v45
	v_fmac_f32_e32 v33, v85, v41
	v_add_f32_e32 v31, v33, v31
	v_mul_f32_e32 v33, v123, v45
	v_fmac_f32_e32 v33, v121, v41
	v_add_f32_e32 v32, v33, v32
	v_mul_f32_e32 v33, v86, v46
	v_fmac_f32_e32 v33, v80, v42
	v_add_f32_e32 v31, v33, v31
	v_mul_f32_e32 v33, v118, v46
	v_fmac_f32_e32 v33, v116, v42
	v_add_f32_e32 v40, v33, v32
	ds_read_b128 v[32:35], v73 offset:45056
	ds_read_b128 v[36:39], v73 offset:46080
	v_mul_f32_e32 v41, v87, v47
	v_fmac_f32_e32 v41, v81, v43
	v_add_f32_e32 v31, v41, v31
	v_mul_f32_e32 v41, v119, v47
	v_fmac_f32_e32 v41, v117, v43
	v_add_f32_e32 v40, v41, v40
	s_waitcnt lgkmcnt(0)
	v_mul_f32_e32 v41, v96, v36
	v_mul_f32_e32 v36, v14, v36
	v_fmac_f32_e32 v36, v12, v32
	v_fmac_f32_e32 v41, v94, v32
	v_add_f32_e32 v32, v36, v40
	v_mul_f32_e32 v36, v97, v37
	v_add_f32_e32 v31, v41, v31
	v_fmac_f32_e32 v36, v95, v33
	v_add_f32_e32 v31, v36, v31
	v_mul_f32_e32 v36, v15, v37
	v_fmac_f32_e32 v36, v13, v33
	v_mul_f32_e32 v33, v92, v38
	v_fmac_f32_e32 v33, v90, v34
	v_add_f32_e32 v31, v33, v31
	v_mul_f32_e32 v33, v10, v38
	v_add_f32_e32 v32, v36, v32
	v_fmac_f32_e32 v33, v8, v34
	ds_read_b128 v[40:43], v73 offset:47104
	ds_read_b128 v[44:47], v73 offset:48128
	v_add_f32_e32 v32, v33, v32
	v_mul_f32_e32 v33, v93, v39
	v_fmac_f32_e32 v33, v91, v35
	v_add_f32_e32 v31, v33, v31
	v_mul_f32_e32 v33, v11, v39
	v_fmac_f32_e32 v33, v9, v35
	v_add_f32_e32 v32, v33, v32
	s_waitcnt lgkmcnt(0)
	v_mul_f32_e32 v33, v106, v44
	v_fmac_f32_e32 v33, v104, v40
	v_add_f32_e32 v31, v33, v31
	v_mul_f32_e32 v33, v20, v44
	v_fmac_f32_e32 v33, v18, v40
	v_add_f32_e32 v32, v33, v32
	v_mul_f32_e32 v33, v107, v45
	v_fmac_f32_e32 v33, v105, v41
	v_add_f32_e32 v31, v33, v31
	v_mul_f32_e32 v33, v21, v45
	v_fmac_f32_e32 v33, v19, v41
	v_add_f32_e32 v32, v33, v32
	v_mul_f32_e32 v33, v102, v46
	v_fmac_f32_e32 v33, v100, v42
	v_add_f32_e32 v31, v33, v31
	v_mul_f32_e32 v33, v6, v46
	v_fmac_f32_e32 v33, v16, v42
	ds_read_b128 v[34:37], v73 offset:49152
	ds_read_b128 v[38:41], v73 offset:50176
	v_add_f32_e32 v33, v33, v32
	v_mul_f32_e32 v32, v103, v47
	v_fmac_f32_e32 v32, v101, v43
	v_add_f32_e32 v32, v32, v31
	v_mul_f32_e32 v31, v7, v47
	v_fmac_f32_e32 v31, v17, v43
	v_add_f32_e32 v31, v31, v33
	s_waitcnt lgkmcnt(0)
	v_mul_f32_e32 v33, v82, v38
	v_mul_f32_e32 v38, v114, v38
	v_fmac_f32_e32 v38, v112, v34
	v_fmac_f32_e32 v33, v78, v34
	v_add_f32_e32 v34, 0, v38
	v_mul_f32_e32 v38, v83, v39
	v_add_f32_e32 v33, 0, v33
	v_fmac_f32_e32 v38, v79, v35
	v_add_f32_e32 v33, v38, v33
	v_mul_f32_e32 v38, v115, v39
	v_fmac_f32_e32 v38, v113, v35
	v_mul_f32_e32 v35, v76, v40
	v_fmac_f32_e32 v35, v74, v36
	v_add_f32_e32 v33, v35, v33
	v_mul_f32_e32 v35, v110, v40
	v_add_f32_e32 v34, v38, v34
	v_fmac_f32_e32 v35, v108, v36
	ds_read_b128 v[42:45], v73 offset:51200
	ds_read_b128 v[46:49], v73 offset:52224
	v_add_f32_e32 v34, v35, v34
	v_mul_f32_e32 v35, v77, v41
	v_fmac_f32_e32 v35, v75, v37
	v_add_f32_e32 v33, v35, v33
	v_mul_f32_e32 v35, v111, v41
	v_fmac_f32_e32 v35, v109, v37
	v_add_f32_e32 v34, v35, v34
	s_waitcnt lgkmcnt(0)
	v_mul_f32_e32 v35, v88, v46
	v_fmac_f32_e32 v35, v84, v42
	v_add_f32_e32 v33, v35, v33
	v_mul_f32_e32 v35, v122, v46
	v_fmac_f32_e32 v35, v120, v42
	v_add_f32_e32 v34, v35, v34
	v_mul_f32_e32 v35, v89, v47
	v_fmac_f32_e32 v35, v85, v43
	v_add_f32_e32 v33, v35, v33
	v_mul_f32_e32 v35, v123, v47
	v_fmac_f32_e32 v35, v121, v43
	v_add_f32_e32 v34, v35, v34
	v_mul_f32_e32 v35, v86, v48
	v_fmac_f32_e32 v35, v80, v44
	v_add_f32_e32 v33, v35, v33
	v_mul_f32_e32 v35, v118, v48
	v_fmac_f32_e32 v35, v116, v44
	v_add_f32_e32 v42, v35, v34
	ds_read_b128 v[34:37], v73 offset:53248
	ds_read_b128 v[38:41], v73 offset:54272
	v_mul_f32_e32 v43, v87, v49
	v_fmac_f32_e32 v43, v81, v45
	v_add_f32_e32 v33, v43, v33
	v_mul_f32_e32 v43, v119, v49
	v_fmac_f32_e32 v43, v117, v45
	v_add_f32_e32 v42, v43, v42
	s_waitcnt lgkmcnt(0)
	v_mul_f32_e32 v43, v96, v38
	v_mul_f32_e32 v38, v14, v38
	v_fmac_f32_e32 v38, v12, v34
	v_fmac_f32_e32 v43, v94, v34
	v_add_f32_e32 v34, v38, v42
	v_mul_f32_e32 v38, v97, v39
	v_add_f32_e32 v33, v43, v33
	v_fmac_f32_e32 v38, v95, v35
	v_add_f32_e32 v33, v38, v33
	v_mul_f32_e32 v38, v15, v39
	v_fmac_f32_e32 v38, v13, v35
	v_mul_f32_e32 v35, v92, v40
	v_fmac_f32_e32 v35, v90, v36
	v_add_f32_e32 v33, v35, v33
	v_mul_f32_e32 v35, v10, v40
	v_add_f32_e32 v34, v38, v34
	v_fmac_f32_e32 v35, v8, v36
	ds_read_b128 v[42:45], v73 offset:55296
	ds_read_b128 v[46:49], v73 offset:56320
	v_add_f32_e32 v34, v35, v34
	v_mul_f32_e32 v35, v93, v41
	v_fmac_f32_e32 v35, v91, v37
	v_add_f32_e32 v33, v35, v33
	v_mul_f32_e32 v35, v11, v41
	v_fmac_f32_e32 v35, v9, v37
	v_add_f32_e32 v34, v35, v34
	s_waitcnt lgkmcnt(0)
; #define LAS __attribute__((address_space(3)))
; template <bool ZP, bool XF32, bool OUT8 = false>
; __device__ __forceinline__ void norm_phase(LAS unsigned char* lds, const void* xin, const float* gain, const float* sh, const float* sc, bf16* hout, const float* wzt, float* zout, int lane, int wave, int vcu, int G) {
;     ...
;         if constexpr (ZP) {
;             float p0[16], p1[16];
; #pragma unroll
;             for (int rr = 0; rr < 16; ++rr) { p0[rr] = 0.f; p1[rr] = 0.f;
; #pragma unroll
;                 for (int j = 0; j < 4; ++j) { const f32x4 w0 = *(const LAS f32x4*)(wl + (((rr * 4 + j) * 2 + 0) * 64 + lane) * 4), w1 = *(const LAS f32x4*)(wl + (((rr * 4 + j) * 2 + 1) * 64 + lane) * 4);
; #pragma unroll
;                     for (int e = 0; e < 4; ++e) { p0[rr] += v[0][j][0][e] * w0[e] + v[0][j][1][e] * w1[e]; p1[rr] += v[1][j][0][e] * w0[e] + v[1][j][1][e] * w1[e]; } } }
	v_mul_f32_e32 v35, v106, v46
	v_fmac_f32_e32 v35, v104, v42
	v_add_f32_e32 v33, v35, v33
	v_mul_f32_e32 v35, v20, v46
	v_fmac_f32_e32 v35, v18, v42
	v_add_f32_e32 v34, v35, v34
	v_mul_f32_e32 v35, v107, v47
	v_fmac_f32_e32 v35, v105, v43
	v_add_f32_e32 v33, v35, v33
	v_mul_f32_e32 v35, v21, v47
	v_fmac_f32_e32 v35, v19, v43
	v_add_f32_e32 v34, v35, v34
	v_mul_f32_e32 v35, v102, v48
	v_fmac_f32_e32 v35, v100, v44
	v_add_f32_e32 v33, v35, v33
	v_mul_f32_e32 v35, v6, v48
	v_fmac_f32_e32 v35, v16, v44
	ds_read_b128 v[36:39], v73 offset:57344
	ds_read_b128 v[40:43], v73 offset:58368
	v_add_f32_e32 v35, v35, v34
	v_mul_f32_e32 v34, v103, v49
	v_fmac_f32_e32 v34, v101, v45
	v_add_f32_e32 v34, v34, v33
	v_mul_f32_e32 v33, v7, v49
	v_fmac_f32_e32 v33, v17, v45
	v_add_f32_e32 v33, v33, v35
	s_waitcnt lgkmcnt(0)
	v_mul_f32_e32 v35, v82, v40
	v_mul_f32_e32 v40, v114, v40
	v_fmac_f32_e32 v40, v112, v36
	v_fmac_f32_e32 v35, v78, v36
	v_add_f32_e32 v36, 0, v40
	v_mul_f32_e32 v40, v83, v41
	v_add_f32_e32 v35, 0, v35
	v_fmac_f32_e32 v40, v79, v37
	v_add_f32_e32 v35, v40, v35
	v_mul_f32_e32 v40, v115, v41
	v_fmac_f32_e32 v40, v113, v37
	v_mul_f32_e32 v37, v76, v42
	v_fmac_f32_e32 v37, v74, v38
	v_add_f32_e32 v35, v37, v35
	v_mul_f32_e32 v37, v110, v42
	v_add_f32_e32 v36, v40, v36
	v_fmac_f32_e32 v37, v108, v38
	ds_read_b128 v[44:47], v73 offset:59392
	ds_read_b128 v[48:51], v73 offset:60416
	v_add_f32_e32 v36, v37, v36
	v_mul_f32_e32 v37, v77, v43
	v_fmac_f32_e32 v37, v75, v39
	v_add_f32_e32 v35, v37, v35
	v_mul_f32_e32 v37, v111, v43
	v_fmac_f32_e32 v37, v109, v39
	v_add_f32_e32 v36, v37, v36
	s_waitcnt lgkmcnt(0)
	v_mul_f32_e32 v37, v88, v48
	v_fmac_f32_e32 v37, v84, v44
	v_add_f32_e32 v35, v37, v35
	v_mul_f32_e32 v37, v122, v48
	v_fmac_f32_e32 v37, v120, v44
	v_add_f32_e32 v36, v37, v36
	v_mul_f32_e32 v37, v89, v49
	v_fmac_f32_e32 v37, v85, v45
	v_add_f32_e32 v35, v37, v35
	v_mul_f32_e32 v37, v123, v49
	v_fmac_f32_e32 v37, v121, v45
	v_add_f32_e32 v36, v37, v36
	v_mul_f32_e32 v37, v86, v50
	v_fmac_f32_e32 v37, v80, v46
	v_add_f32_e32 v35, v37, v35
	v_mul_f32_e32 v37, v118, v50
	v_fmac_f32_e32 v37, v116, v46
	v_add_f32_e32 v44, v37, v36
	ds_read_b128 v[36:39], v73 offset:61440
	ds_read_b128 v[40:43], v73 offset:62464
	v_mul_f32_e32 v45, v87, v51
	v_fmac_f32_e32 v45, v81, v47
	v_add_f32_e32 v35, v45, v35
	v_mul_f32_e32 v45, v119, v51
	v_fmac_f32_e32 v45, v117, v47
	v_add_f32_e32 v44, v45, v44
	s_waitcnt lgkmcnt(0)
	v_mul_f32_e32 v45, v96, v40
	v_mul_f32_e32 v40, v14, v40
	v_fmac_f32_e32 v40, v12, v36
	v_fmac_f32_e32 v45, v94, v36
	v_add_f32_e32 v36, v40, v44
	v_mul_f32_e32 v40, v97, v41
	v_add_f32_e32 v35, v45, v35
	v_fmac_f32_e32 v40, v95, v37
	v_add_f32_e32 v35, v40, v35
	v_mul_f32_e32 v40, v15, v41
	v_fmac_f32_e32 v40, v13, v37
	v_mul_f32_e32 v37, v92, v42
	v_fmac_f32_e32 v37, v90, v38
	v_add_f32_e32 v35, v37, v35
	v_mul_f32_e32 v37, v10, v42
	v_add_f32_e32 v36, v40, v36
	v_fmac_f32_e32 v37, v8, v38
	ds_read_b128 v[44:47], v73 offset:63488
	ds_read_b128 v[48:51], v73 offset:64512
	v_add_f32_e32 v36, v37, v36
	v_mul_f32_e32 v37, v93, v43
	v_fmac_f32_e32 v37, v91, v39
	v_add_f32_e32 v35, v37, v35
	v_mul_f32_e32 v37, v11, v43
	v_fmac_f32_e32 v37, v9, v39
	v_add_f32_e32 v36, v37, v36
	s_waitcnt lgkmcnt(0)
	v_mul_f32_e32 v37, v106, v48
	v_fmac_f32_e32 v37, v104, v44
	v_add_f32_e32 v35, v37, v35
	v_mul_f32_e32 v37, v20, v48
	v_fmac_f32_e32 v37, v18, v44
	v_add_f32_e32 v36, v37, v36
	v_mul_f32_e32 v37, v107, v49
	v_fmac_f32_e32 v37, v105, v45
	v_add_f32_e32 v35, v37, v35
	v_mul_f32_e32 v37, v21, v49
	v_fmac_f32_e32 v37, v19, v45
	v_add_f32_e32 v36, v37, v36
	v_mul_f32_e32 v37, v102, v50
	v_fmac_f32_e32 v37, v100, v46
	v_add_f32_e32 v35, v37, v35
	v_mul_f32_e32 v37, v6, v50
	v_fmac_f32_e32 v37, v16, v46
	ds_read_b128 v[38:41], v149
	ds_read_b128 v[42:45], v150
	v_add_f32_e32 v37, v37, v36
	v_mul_f32_e32 v36, v103, v51
	v_fmac_f32_e32 v36, v101, v47
	v_add_f32_e32 v36, v36, v35
	v_mul_f32_e32 v35, v7, v51
	v_fmac_f32_e32 v35, v17, v47
	v_add_f32_e32 v35, v35, v37
	s_waitcnt lgkmcnt(0)
	v_mul_f32_e32 v37, v82, v42
	v_mul_f32_e32 v42, v114, v42
	v_fmac_f32_e32 v42, v112, v38
	v_fmac_f32_e32 v37, v78, v38
	v_add_f32_e32 v38, 0, v42
	v_mul_f32_e32 v42, v83, v43
	v_add_f32_e32 v37, 0, v37
	v_fmac_f32_e32 v42, v79, v39
	v_add_f32_e32 v37, v42, v37
	v_mul_f32_e32 v42, v115, v43
	v_fmac_f32_e32 v42, v113, v39
	v_mul_f32_e32 v39, v76, v44
	v_fmac_f32_e32 v39, v74, v40
	v_add_f32_e32 v37, v39, v37
	v_mul_f32_e32 v39, v110, v44
	v_add_f32_e32 v38, v42, v38
	v_fmac_f32_e32 v39, v108, v40
	ds_read_b128 v[46:49], v151
	ds_read_b128 v[50:53], v152
	v_add_f32_e32 v38, v39, v38
	v_mul_f32_e32 v39, v77, v45
	v_fmac_f32_e32 v39, v75, v41
	v_add_f32_e32 v37, v39, v37
	v_mul_f32_e32 v39, v111, v45
	v_fmac_f32_e32 v39, v109, v41
	v_add_f32_e32 v38, v39, v38
	s_waitcnt lgkmcnt(0)
	v_mul_f32_e32 v39, v88, v50
	v_fmac_f32_e32 v39, v84, v46
	v_add_f32_e32 v37, v39, v37
	v_mul_f32_e32 v39, v122, v50
	v_fmac_f32_e32 v39, v120, v46
	v_add_f32_e32 v38, v39, v38
	v_mul_f32_e32 v39, v89, v51
	v_fmac_f32_e32 v39, v85, v47
	v_add_f32_e32 v37, v39, v37
	v_mul_f32_e32 v39, v123, v51
	v_fmac_f32_e32 v39, v121, v47
	v_add_f32_e32 v38, v39, v38
	v_mul_f32_e32 v39, v86, v52
	v_fmac_f32_e32 v39, v80, v48
	v_add_f32_e32 v37, v39, v37
	v_mul_f32_e32 v39, v118, v52
	v_fmac_f32_e32 v39, v116, v48
	v_add_f32_e32 v46, v39, v38
	ds_read_b128 v[38:41], v153
	ds_read_b128 v[42:45], v154
	v_mul_f32_e32 v47, v87, v53
	v_fmac_f32_e32 v47, v81, v49
	v_add_f32_e32 v37, v47, v37
	v_mul_f32_e32 v47, v119, v53
	v_fmac_f32_e32 v47, v117, v49
	v_add_f32_e32 v46, v47, v46
	s_waitcnt lgkmcnt(0)
; #define LAS __attribute__((address_space(3)))
; template <bool ZP, bool XF32, bool OUT8 = false>
; __device__ __forceinline__ void norm_phase(LAS unsigned char* lds, const void* xin, const float* gain, const float* sh, const float* sc, bf16* hout, const float* wzt, float* zout, int lane, int wave, int vcu, int G) {
;     ...
;         if constexpr (ZP) {
;             float p0[16], p1[16];
; #pragma unroll
;             for (int rr = 0; rr < 16; ++rr) { p0[rr] = 0.f; p1[rr] = 0.f;
; #pragma unroll
;                 for (int j = 0; j < 4; ++j) { const f32x4 w0 = *(const LAS f32x4*)(wl + (((rr * 4 + j) * 2 + 0) * 64 + lane) * 4), w1 = *(const LAS f32x4*)(wl + (((rr * 4 + j) * 2 + 1) * 64 + lane) * 4);
; #pragma unroll
;                     for (int e = 0; e < 4; ++e) { p0[rr] += v[0][j][0][e] * w0[e] + v[0][j][1][e] * w1[e]; p1[rr] += v[1][j][0][e] * w0[e] + v[1][j][1][e] * w1[e]; } } }
	v_mul_f32_e32 v47, v96, v42
	v_mul_f32_e32 v42, v14, v42
	v_fmac_f32_e32 v42, v12, v38
	v_fmac_f32_e32 v47, v94, v38
	v_add_f32_e32 v38, v42, v46
	v_mul_f32_e32 v42, v97, v43
	v_add_f32_e32 v37, v47, v37
	v_fmac_f32_e32 v42, v95, v39
	v_add_f32_e32 v37, v42, v37
	v_mul_f32_e32 v42, v15, v43
	v_fmac_f32_e32 v42, v13, v39
	v_mul_f32_e32 v39, v92, v44
	v_fmac_f32_e32 v39, v90, v40
	v_add_f32_e32 v37, v39, v37
	v_mul_f32_e32 v39, v10, v44
	v_add_f32_e32 v38, v42, v38
	v_fmac_f32_e32 v39, v8, v40
	ds_read_b128 v[46:49], v155
	ds_read_b128 v[50:53], v156
	v_add_f32_e32 v38, v39, v38
	v_mul_f32_e32 v39, v93, v45
	v_fmac_f32_e32 v39, v91, v41
	v_add_f32_e32 v37, v39, v37
	v_mul_f32_e32 v39, v11, v45
	v_fmac_f32_e32 v39, v9, v41
	v_add_f32_e32 v38, v39, v38
	s_waitcnt lgkmcnt(0)
	v_mul_f32_e32 v39, v106, v50
	v_fmac_f32_e32 v39, v104, v46
	v_add_f32_e32 v37, v39, v37
	v_mul_f32_e32 v39, v20, v50
	v_fmac_f32_e32 v39, v18, v46
	v_add_f32_e32 v38, v39, v38
	v_mul_f32_e32 v39, v107, v51
	v_fmac_f32_e32 v39, v105, v47
	v_add_f32_e32 v37, v39, v37
	v_mul_f32_e32 v39, v21, v51
	v_fmac_f32_e32 v39, v19, v47
	v_add_f32_e32 v38, v39, v38
	v_mul_f32_e32 v39, v102, v52
	v_fmac_f32_e32 v39, v100, v48
	v_add_f32_e32 v37, v39, v37
	v_mul_f32_e32 v39, v6, v52
	v_fmac_f32_e32 v39, v16, v48
	ds_read_b128 v[40:43], v157
	ds_read_b128 v[44:47], v158
	v_add_f32_e32 v39, v39, v38
	v_mul_f32_e32 v38, v103, v53
	v_fmac_f32_e32 v38, v101, v49
	v_add_f32_e32 v38, v38, v37
	v_mul_f32_e32 v37, v7, v53
	v_fmac_f32_e32 v37, v17, v49
	v_add_f32_e32 v37, v37, v39
	s_waitcnt lgkmcnt(0)
	v_mul_f32_e32 v39, v82, v44
	v_mul_f32_e32 v44, v114, v44
	v_fmac_f32_e32 v44, v112, v40
	v_fmac_f32_e32 v39, v78, v40
	v_add_f32_e32 v40, 0, v44
	v_mul_f32_e32 v44, v83, v45
	v_add_f32_e32 v39, 0, v39
	v_fmac_f32_e32 v44, v79, v41
	v_add_f32_e32 v39, v44, v39
	v_mul_f32_e32 v44, v115, v45
	v_fmac_f32_e32 v44, v113, v41
	v_mul_f32_e32 v41, v76, v46
	v_fmac_f32_e32 v41, v74, v42
	v_add_f32_e32 v39, v41, v39
	v_mul_f32_e32 v41, v110, v46
	v_add_f32_e32 v40, v44, v40
	v_fmac_f32_e32 v41, v108, v42
	ds_read_b128 v[48:51], v159
	ds_read_b128 v[52:55], v160
	v_add_f32_e32 v40, v41, v40
	v_mul_f32_e32 v41, v77, v47
	v_fmac_f32_e32 v41, v75, v43
	v_add_f32_e32 v39, v41, v39
	v_mul_f32_e32 v41, v111, v47
	v_fmac_f32_e32 v41, v109, v43
	v_add_f32_e32 v40, v41, v40
	s_waitcnt lgkmcnt(0)
	v_mul_f32_e32 v41, v88, v52
	v_fmac_f32_e32 v41, v84, v48
	v_add_f32_e32 v39, v41, v39
	v_mul_f32_e32 v41, v122, v52
	v_fmac_f32_e32 v41, v120, v48
	v_add_f32_e32 v40, v41, v40
	v_mul_f32_e32 v41, v89, v53
	v_fmac_f32_e32 v41, v85, v49
	v_add_f32_e32 v39, v41, v39
	v_mul_f32_e32 v41, v123, v53
	v_fmac_f32_e32 v41, v121, v49
	v_add_f32_e32 v40, v41, v40
	v_mul_f32_e32 v41, v86, v54
	v_fmac_f32_e32 v41, v80, v50
	v_add_f32_e32 v39, v41, v39
	v_mul_f32_e32 v41, v118, v54
	v_fmac_f32_e32 v41, v116, v50
	v_add_f32_e32 v48, v41, v40
	ds_read_b128 v[40:43], v161
	ds_read_b128 v[44:47], v162
	v_mul_f32_e32 v49, v87, v55
	v_fmac_f32_e32 v49, v81, v51
	v_add_f32_e32 v39, v49, v39
	v_mul_f32_e32 v49, v119, v55
	v_fmac_f32_e32 v49, v117, v51
	v_add_f32_e32 v48, v49, v48
	s_waitcnt lgkmcnt(0)
	v_mul_f32_e32 v49, v96, v44
	v_mul_f32_e32 v44, v14, v44
	v_fmac_f32_e32 v44, v12, v40
	v_fmac_f32_e32 v49, v94, v40
	v_add_f32_e32 v40, v44, v48
	v_mul_f32_e32 v44, v97, v45
	v_add_f32_e32 v39, v49, v39
	v_fmac_f32_e32 v44, v95, v41
	v_add_f32_e32 v39, v44, v39
	v_mul_f32_e32 v44, v15, v45
	v_fmac_f32_e32 v44, v13, v41
	v_mul_f32_e32 v41, v92, v46
	v_fmac_f32_e32 v41, v90, v42
	v_add_f32_e32 v39, v41, v39
	v_mul_f32_e32 v41, v10, v46
	v_add_f32_e32 v40, v44, v40
	v_fmac_f32_e32 v41, v8, v42
	ds_read_b128 v[48:51], v163
	ds_read_b128 v[52:55], v164
	v_add_f32_e32 v40, v41, v40
	v_mul_f32_e32 v41, v93, v47
	v_fmac_f32_e32 v41, v91, v43
	v_add_f32_e32 v39, v41, v39
	v_mul_f32_e32 v41, v11, v47
	v_fmac_f32_e32 v41, v9, v43
	v_add_f32_e32 v40, v41, v40
	s_waitcnt lgkmcnt(0)
	v_mul_f32_e32 v41, v106, v52
	v_fmac_f32_e32 v41, v104, v48
	v_add_f32_e32 v39, v41, v39
	v_mul_f32_e32 v41, v20, v52
	v_fmac_f32_e32 v41, v18, v48
	v_add_f32_e32 v40, v41, v40
	v_mul_f32_e32 v41, v107, v53
	v_fmac_f32_e32 v41, v105, v49
	v_add_f32_e32 v39, v41, v39
	v_mul_f32_e32 v41, v21, v53
	v_fmac_f32_e32 v41, v19, v49
	v_add_f32_e32 v40, v41, v40
	v_mul_f32_e32 v41, v102, v54
	v_fmac_f32_e32 v41, v100, v50
	v_add_f32_e32 v39, v41, v39
	v_mul_f32_e32 v41, v6, v54
	v_fmac_f32_e32 v41, v16, v50
	ds_read_b128 v[42:45], v165
	ds_read_b128 v[46:49], v166
	v_add_f32_e32 v41, v41, v40
	v_mul_f32_e32 v40, v103, v55
	v_fmac_f32_e32 v40, v101, v51
	v_add_f32_e32 v40, v40, v39
	v_mul_f32_e32 v39, v7, v55
	v_fmac_f32_e32 v39, v17, v51
	v_add_f32_e32 v39, v39, v41
	s_waitcnt lgkmcnt(0)
	v_mul_f32_e32 v41, v82, v46
	v_mul_f32_e32 v46, v114, v46
	v_fmac_f32_e32 v46, v112, v42
	v_fmac_f32_e32 v41, v78, v42
	v_add_f32_e32 v42, 0, v46
	v_mul_f32_e32 v46, v83, v47
	v_add_f32_e32 v41, 0, v41
	v_fmac_f32_e32 v46, v79, v43
	v_add_f32_e32 v41, v46, v41
	v_mul_f32_e32 v46, v115, v47
	v_fmac_f32_e32 v46, v113, v43
	v_mul_f32_e32 v43, v76, v48
	v_fmac_f32_e32 v43, v74, v44
	v_add_f32_e32 v41, v43, v41
	v_mul_f32_e32 v43, v110, v48
	v_add_f32_e32 v42, v46, v42
	v_fmac_f32_e32 v43, v108, v44
	ds_read_b128 v[50:53], v167
	ds_read_b128 v[54:57], v168
	v_add_f32_e32 v42, v43, v42
	v_mul_f32_e32 v43, v77, v49
	v_fmac_f32_e32 v43, v75, v45
	v_add_f32_e32 v41, v43, v41
	v_mul_f32_e32 v43, v111, v49
	v_fmac_f32_e32 v43, v109, v45
	v_add_f32_e32 v42, v43, v42
	s_waitcnt lgkmcnt(0)
; #define LAS __attribute__((address_space(3)))
; template <bool ZP, bool XF32, bool OUT8 = false>
; __device__ __forceinline__ void norm_phase(LAS unsigned char* lds, const void* xin, const float* gain, const float* sh, const float* sc, bf16* hout, const float* wzt, float* zout, int lane, int wave, int vcu, int G) {
;     ...
;         if constexpr (ZP) {
;             float p0[16], p1[16];
; #pragma unroll
;             for (int rr = 0; rr < 16; ++rr) { p0[rr] = 0.f; p1[rr] = 0.f;
; #pragma unroll
;                 for (int j = 0; j < 4; ++j) { const f32x4 w0 = *(const LAS f32x4*)(wl + (((rr * 4 + j) * 2 + 0) * 64 + lane) * 4), w1 = *(const LAS f32x4*)(wl + (((rr * 4 + j) * 2 + 1) * 64 + lane) * 4);
; #pragma unroll
;                     for (int e = 0; e < 4; ++e) { p0[rr] += v[0][j][0][e] * w0[e] + v[0][j][1][e] * w1[e]; p1[rr] += v[1][j][0][e] * w0[e] + v[1][j][1][e] * w1[e]; } } }
	v_mul_f32_e32 v43, v88, v54
	v_fmac_f32_e32 v43, v84, v50
	v_add_f32_e32 v41, v43, v41
	v_mul_f32_e32 v43, v122, v54
	v_fmac_f32_e32 v43, v120, v50
	v_add_f32_e32 v42, v43, v42
	v_mul_f32_e32 v43, v89, v55
	v_fmac_f32_e32 v43, v85, v51
	v_add_f32_e32 v41, v43, v41
	v_mul_f32_e32 v43, v123, v55
	v_fmac_f32_e32 v43, v121, v51
	v_add_f32_e32 v42, v43, v42
	v_mul_f32_e32 v43, v86, v56
	v_fmac_f32_e32 v43, v80, v52
	v_add_f32_e32 v41, v43, v41
	v_mul_f32_e32 v43, v118, v56
	v_fmac_f32_e32 v43, v116, v52
	v_add_f32_e32 v50, v43, v42
	ds_read_b128 v[42:45], v169
	ds_read_b128 v[46:49], v170
	v_mul_f32_e32 v51, v87, v57
	v_fmac_f32_e32 v51, v81, v53
	v_add_f32_e32 v41, v51, v41
	v_mul_f32_e32 v51, v119, v57
	v_fmac_f32_e32 v51, v117, v53
	v_add_f32_e32 v50, v51, v50
	s_waitcnt lgkmcnt(0)
	v_mul_f32_e32 v51, v96, v46
	v_mul_f32_e32 v46, v14, v46
	v_fmac_f32_e32 v46, v12, v42
	v_fmac_f32_e32 v51, v94, v42
	v_add_f32_e32 v42, v46, v50
	v_mul_f32_e32 v46, v97, v47
	v_add_f32_e32 v41, v51, v41
	v_fmac_f32_e32 v46, v95, v43
	v_add_f32_e32 v41, v46, v41
	v_mul_f32_e32 v46, v15, v47
	v_fmac_f32_e32 v46, v13, v43
	v_mul_f32_e32 v43, v92, v48
	v_fmac_f32_e32 v43, v90, v44
	v_add_f32_e32 v41, v43, v41
	v_mul_f32_e32 v43, v10, v48
	v_add_f32_e32 v42, v46, v42
	v_fmac_f32_e32 v43, v8, v44
	ds_read_b128 v[50:53], v171
	ds_read_b128 v[54:57], v172
	v_add_f32_e32 v42, v43, v42
	v_mul_f32_e32 v43, v93, v49
	v_fmac_f32_e32 v43, v91, v45
	v_add_f32_e32 v41, v43, v41
	v_mul_f32_e32 v43, v11, v49
	v_fmac_f32_e32 v43, v9, v45
	v_add_f32_e32 v42, v43, v42
	s_waitcnt lgkmcnt(0)
	v_mul_f32_e32 v43, v106, v54
	v_fmac_f32_e32 v43, v104, v50
	v_add_f32_e32 v41, v43, v41
	v_mul_f32_e32 v43, v20, v54
	v_fmac_f32_e32 v43, v18, v50
	v_add_f32_e32 v42, v43, v42
	v_mul_f32_e32 v43, v107, v55
	v_fmac_f32_e32 v43, v105, v51
	v_add_f32_e32 v41, v43, v41
	v_mul_f32_e32 v43, v21, v55
	v_fmac_f32_e32 v43, v19, v51
	v_add_f32_e32 v42, v43, v42
	v_mul_f32_e32 v43, v102, v56
	v_fmac_f32_e32 v43, v100, v52
	v_add_f32_e32 v41, v43, v41
	v_mul_f32_e32 v43, v6, v56
	v_fmac_f32_e32 v43, v16, v52
	ds_read_b128 v[44:47], v173
	ds_read_b128 v[48:51], v174
	v_add_f32_e32 v43, v43, v42
	v_mul_f32_e32 v42, v103, v57
	v_fmac_f32_e32 v42, v101, v53
	v_add_f32_e32 v42, v42, v41
	v_mul_f32_e32 v41, v7, v57
	v_fmac_f32_e32 v41, v17, v53
	v_add_f32_e32 v41, v41, v43
	s_waitcnt lgkmcnt(0)
	v_mul_f32_e32 v43, v82, v48
	v_mul_f32_e32 v48, v114, v48
	v_fmac_f32_e32 v48, v112, v44
	v_fmac_f32_e32 v43, v78, v44
	v_add_f32_e32 v44, 0, v48
	v_mul_f32_e32 v48, v83, v49
	v_add_f32_e32 v43, 0, v43
	v_fmac_f32_e32 v48, v79, v45
	v_add_f32_e32 v43, v48, v43
	v_mul_f32_e32 v48, v115, v49
	v_fmac_f32_e32 v48, v113, v45
	v_mul_f32_e32 v45, v76, v50
	v_fmac_f32_e32 v45, v74, v46
	v_add_f32_e32 v43, v45, v43
	v_mul_f32_e32 v45, v110, v50
	v_add_f32_e32 v44, v48, v44
	v_fmac_f32_e32 v45, v108, v46
	ds_read_b128 v[52:55], v175
	ds_read_b128 v[124:127], v176
	v_add_f32_e32 v44, v45, v44
	v_mul_f32_e32 v45, v77, v51
	v_fmac_f32_e32 v45, v75, v47
	v_add_f32_e32 v43, v45, v43
	v_mul_f32_e32 v45, v111, v51
	v_fmac_f32_e32 v45, v109, v47
	v_add_f32_e32 v44, v45, v44
	s_waitcnt lgkmcnt(0)
	v_mul_f32_e32 v45, v88, v124
	v_fmac_f32_e32 v45, v84, v52
	v_add_f32_e32 v43, v45, v43
	v_mul_f32_e32 v45, v122, v124
	v_fmac_f32_e32 v45, v120, v52
	v_add_f32_e32 v44, v45, v44
	v_mul_f32_e32 v45, v89, v125
	v_fmac_f32_e32 v45, v85, v53
	v_add_f32_e32 v43, v45, v43
	v_mul_f32_e32 v45, v123, v125
	v_fmac_f32_e32 v45, v121, v53
	v_add_f32_e32 v44, v45, v44
	v_mul_f32_e32 v45, v86, v126
	v_fmac_f32_e32 v45, v80, v54
	v_add_f32_e32 v43, v45, v43
	v_mul_f32_e32 v45, v118, v126
	v_fmac_f32_e32 v45, v116, v54
	v_add_f32_e32 v52, v45, v44
	ds_read_b128 v[44:47], v177
	ds_read_b128 v[48:51], v178
	v_mul_f32_e32 v53, v87, v127
	v_fmac_f32_e32 v53, v81, v55
	v_add_f32_e32 v43, v53, v43
	v_mul_f32_e32 v53, v119, v127
	v_fmac_f32_e32 v53, v117, v55
	v_add_f32_e32 v52, v53, v52
	s_waitcnt lgkmcnt(0)
	v_mul_f32_e32 v53, v96, v48
	v_mul_f32_e32 v48, v14, v48
	v_fmac_f32_e32 v48, v12, v44
	v_fmac_f32_e32 v53, v94, v44
	v_add_f32_e32 v44, v48, v52
	v_mul_f32_e32 v48, v97, v49
	v_add_f32_e32 v43, v53, v43
	v_fmac_f32_e32 v48, v95, v45
	v_add_f32_e32 v43, v48, v43
	v_mul_f32_e32 v48, v15, v49
	v_fmac_f32_e32 v48, v13, v45
	v_mul_f32_e32 v45, v92, v50
	v_fmac_f32_e32 v45, v90, v46
	v_add_f32_e32 v43, v45, v43
	v_mul_f32_e32 v45, v10, v50
	v_add_f32_e32 v44, v48, v44
	v_fmac_f32_e32 v45, v8, v46
	ds_read_b128 v[52:55], v179
	ds_read_b128 v[124:127], v180
	v_add_f32_e32 v44, v45, v44
	v_mul_f32_e32 v45, v93, v51
	v_fmac_f32_e32 v45, v91, v47
	v_add_f32_e32 v43, v45, v43
	v_mul_f32_e32 v45, v11, v51
	v_fmac_f32_e32 v45, v9, v47
	v_add_f32_e32 v44, v45, v44
	s_waitcnt lgkmcnt(0)
	v_mul_f32_e32 v45, v106, v124
	v_fmac_f32_e32 v45, v104, v52
	v_add_f32_e32 v43, v45, v43
	v_mul_f32_e32 v45, v20, v124
	v_fmac_f32_e32 v45, v18, v52
	v_add_f32_e32 v44, v45, v44
	v_mul_f32_e32 v45, v107, v125
	v_fmac_f32_e32 v45, v105, v53
	v_add_f32_e32 v43, v45, v43
	v_mul_f32_e32 v45, v21, v125
	v_fmac_f32_e32 v45, v19, v53
	v_add_f32_e32 v44, v45, v44
	v_mul_f32_e32 v45, v102, v126
	v_fmac_f32_e32 v45, v100, v54
	v_add_f32_e32 v43, v45, v43
	v_mul_f32_e32 v45, v6, v126
	v_fmac_f32_e32 v45, v16, v54
	ds_read_b128 v[46:49], v181
	ds_read_b128 v[50:53], v182
	v_add_f32_e32 v45, v45, v44
	v_mul_f32_e32 v44, v103, v127
	v_fmac_f32_e32 v44, v101, v55
	v_add_f32_e32 v44, v44, v43
	v_mul_f32_e32 v43, v7, v127
	v_fmac_f32_e32 v43, v17, v55
	v_add_f32_e32 v43, v43, v45
	s_waitcnt lgkmcnt(0)
; #define LAS __attribute__((address_space(3)))
; template <bool ZP, bool XF32, bool OUT8 = false>
; __device__ __forceinline__ void norm_phase(LAS unsigned char* lds, const void* xin, const float* gain, const float* sh, const float* sc, bf16* hout, const float* wzt, float* zout, int lane, int wave, int vcu, int G) {
;     ...
;         if constexpr (ZP) {
;             float p0[16], p1[16];
; #pragma unroll
;             for (int rr = 0; rr < 16; ++rr) { p0[rr] = 0.f; p1[rr] = 0.f;
; #pragma unroll
;                 for (int j = 0; j < 4; ++j) { const f32x4 w0 = *(const LAS f32x4*)(wl + (((rr * 4 + j) * 2 + 0) * 64 + lane) * 4), w1 = *(const LAS f32x4*)(wl + (((rr * 4 + j) * 2 + 1) * 64 + lane) * 4);
; #pragma unroll
;                     for (int e = 0; e < 4; ++e) { p0[rr] += v[0][j][0][e] * w0[e] + v[0][j][1][e] * w1[e]; p1[rr] += v[1][j][0][e] * w0[e] + v[1][j][1][e] * w1[e]; } } }
	v_mul_f32_e32 v45, v82, v50
	v_mul_f32_e32 v50, v114, v50
	v_fmac_f32_e32 v50, v112, v46
	v_fmac_f32_e32 v45, v78, v46
	v_add_f32_e32 v46, 0, v50
	v_mul_f32_e32 v50, v83, v51
	v_add_f32_e32 v45, 0, v45
	v_fmac_f32_e32 v50, v79, v47
	v_add_f32_e32 v45, v50, v45
	v_mul_f32_e32 v50, v115, v51
	v_fmac_f32_e32 v50, v113, v47
	v_mul_f32_e32 v47, v76, v52
	v_fmac_f32_e32 v47, v74, v48
	v_add_f32_e32 v45, v47, v45
	v_mul_f32_e32 v47, v110, v52
	v_add_f32_e32 v46, v50, v46
	v_fmac_f32_e32 v47, v108, v48
	ds_read_b128 v[54:57], v183
	ds_read_b128 v[124:127], v184
	v_add_f32_e32 v46, v47, v46
	v_mul_f32_e32 v47, v77, v53
	v_fmac_f32_e32 v47, v75, v49
	v_add_f32_e32 v45, v47, v45
	v_mul_f32_e32 v47, v111, v53
	v_fmac_f32_e32 v47, v109, v49
	v_add_f32_e32 v46, v47, v46
	s_waitcnt lgkmcnt(0)
	v_mul_f32_e32 v47, v88, v124
	v_fmac_f32_e32 v47, v84, v54
	v_add_f32_e32 v45, v47, v45
	v_mul_f32_e32 v47, v122, v124
	v_fmac_f32_e32 v47, v120, v54
	v_add_f32_e32 v46, v47, v46
	v_mul_f32_e32 v47, v89, v125
	v_fmac_f32_e32 v47, v85, v55
	v_add_f32_e32 v45, v47, v45
	v_mul_f32_e32 v47, v123, v125
	v_fmac_f32_e32 v47, v121, v55
	v_add_f32_e32 v46, v47, v46
	v_mul_f32_e32 v47, v86, v126
	v_fmac_f32_e32 v47, v80, v56
	v_add_f32_e32 v45, v47, v45
	v_mul_f32_e32 v47, v118, v126
	v_fmac_f32_e32 v47, v116, v56
	v_add_f32_e32 v54, v47, v46
	ds_read_b128 v[46:49], v185
	ds_read_b128 v[50:53], v186
	v_mul_f32_e32 v55, v87, v127
	v_fmac_f32_e32 v55, v81, v57
	v_add_f32_e32 v45, v55, v45
	v_mul_f32_e32 v55, v119, v127
	v_fmac_f32_e32 v55, v117, v57
	v_add_f32_e32 v54, v55, v54
	s_waitcnt lgkmcnt(0)
	v_mul_f32_e32 v55, v96, v50
	v_mul_f32_e32 v50, v14, v50
	v_fmac_f32_e32 v50, v12, v46
	v_fmac_f32_e32 v55, v94, v46
	v_add_f32_e32 v46, v50, v54
	v_mul_f32_e32 v50, v97, v51
	v_add_f32_e32 v45, v55, v45
	v_fmac_f32_e32 v50, v95, v47
	v_add_f32_e32 v45, v50, v45
	v_mul_f32_e32 v50, v15, v51
	v_fmac_f32_e32 v50, v13, v47
	v_mul_f32_e32 v47, v92, v52
	v_fmac_f32_e32 v47, v90, v48
	v_add_f32_e32 v45, v47, v45
	v_mul_f32_e32 v47, v10, v52
	v_add_f32_e32 v46, v50, v46
	v_fmac_f32_e32 v47, v8, v48
	ds_read_b128 v[54:57], v187
	ds_read_b128 v[124:127], v188
	v_add_f32_e32 v46, v47, v46
	v_mul_f32_e32 v47, v93, v53
	v_fmac_f32_e32 v47, v91, v49
	v_add_f32_e32 v45, v47, v45
	v_mul_f32_e32 v47, v11, v53
	v_fmac_f32_e32 v47, v9, v49
	v_add_f32_e32 v46, v47, v46
	s_waitcnt lgkmcnt(0)
	v_mul_f32_e32 v47, v106, v124
	v_fmac_f32_e32 v47, v104, v54
	v_add_f32_e32 v45, v47, v45
	v_mul_f32_e32 v47, v20, v124
	v_fmac_f32_e32 v47, v18, v54
	v_add_f32_e32 v46, v47, v46
	v_mul_f32_e32 v47, v107, v125
	v_fmac_f32_e32 v47, v105, v55
	v_add_f32_e32 v45, v47, v45
	v_mul_f32_e32 v47, v21, v125
	v_fmac_f32_e32 v47, v19, v55
	v_add_f32_e32 v46, v47, v46
	v_mul_f32_e32 v47, v102, v126
	v_fmac_f32_e32 v47, v100, v56
	v_add_f32_e32 v45, v47, v45
	v_mul_f32_e32 v47, v6, v126
	v_fmac_f32_e32 v47, v16, v56
	v_add_f32_e32 v54, v47, v46
	ds_read_b128 v[46:49], v189
	ds_read_b128 v[50:53], v190
	v_mul_f32_e32 v55, v103, v127
	v_fmac_f32_e32 v55, v101, v57
	v_add_f32_e32 v128, v55, v45
	v_mul_f32_e32 v45, v7, v127
	v_fmac_f32_e32 v45, v17, v57
	v_add_f32_e32 v45, v45, v54
	s_waitcnt lgkmcnt(0)
	v_mul_f32_e32 v54, v82, v50
	v_mul_f32_e32 v50, v114, v50
	v_fmac_f32_e32 v50, v112, v46
	v_fmac_f32_e32 v54, v78, v46
	v_add_f32_e32 v46, 0, v50
	v_mul_f32_e32 v50, v83, v51
	v_mul_f32_e32 v51, v115, v51
	v_add_f32_e32 v54, 0, v54
	v_fmac_f32_e32 v50, v79, v47
	v_fmac_f32_e32 v51, v113, v47
	v_mul_f32_e32 v47, v76, v52
	v_add_f32_e32 v50, v50, v54
	v_fmac_f32_e32 v47, v74, v48
	v_add_f32_e32 v47, v47, v50
	v_mul_f32_e32 v50, v110, v52
	ds_read_b128 v[54:57], v191
	ds_read_b128 v[124:127], v192
	v_fmac_f32_e32 v50, v108, v48
	v_mul_f32_e32 v48, v77, v53
	v_fmac_f32_e32 v48, v75, v49
	v_add_f32_e32 v46, v51, v46
	v_add_f32_e32 v47, v48, v47
	v_mul_f32_e32 v48, v111, v53
	v_add_f32_e32 v46, v50, v46
	v_fmac_f32_e32 v48, v109, v49
	v_add_f32_e32 v46, v48, v46
	s_waitcnt lgkmcnt(0)
	v_mul_f32_e32 v48, v88, v124
	v_fmac_f32_e32 v48, v84, v54
	v_add_f32_e32 v47, v48, v47
	v_mul_f32_e32 v48, v122, v124
	v_fmac_f32_e32 v48, v120, v54
	v_add_f32_e32 v46, v48, v46
	v_mul_f32_e32 v48, v89, v125
	v_fmac_f32_e32 v48, v85, v55
	v_add_f32_e32 v47, v48, v47
	v_mul_f32_e32 v48, v123, v125
	v_fmac_f32_e32 v48, v121, v55
	v_add_f32_e32 v46, v48, v46
	v_mul_f32_e32 v48, v86, v126
	v_fmac_f32_e32 v48, v80, v56
	v_add_f32_e32 v54, v48, v47
	v_mul_f32_e32 v47, v118, v126
	v_fmac_f32_e32 v47, v116, v56
	v_add_f32_e32 v55, v47, v46
	ds_read_b128 v[46:49], v193
	ds_read_b128 v[50:53], v194
	v_mul_f32_e32 v56, v87, v127
	v_fmac_f32_e32 v56, v81, v57
	v_add_f32_e32 v54, v56, v54
	v_mul_f32_e32 v56, v119, v127
	v_fmac_f32_e32 v56, v117, v57
	v_add_f32_e32 v55, v56, v55
	s_waitcnt lgkmcnt(0)
	v_mul_f32_e32 v56, v96, v50
	v_mul_f32_e32 v50, v14, v50
	v_fmac_f32_e32 v50, v12, v46
	v_fmac_f32_e32 v56, v94, v46
	v_add_f32_e32 v46, v50, v55
	v_mul_f32_e32 v50, v97, v51
	v_mul_f32_e32 v51, v15, v51
	v_add_f32_e32 v54, v56, v54
	v_fmac_f32_e32 v50, v95, v47
	v_fmac_f32_e32 v51, v13, v47
	v_mul_f32_e32 v47, v92, v52
	v_add_f32_e32 v50, v50, v54
	v_fmac_f32_e32 v47, v90, v48
	v_add_f32_e32 v47, v47, v50
	v_mul_f32_e32 v50, v10, v52
	ds_read_b128 v[54:57], v195
	ds_read_b128 v[124:127], v196
	v_fmac_f32_e32 v50, v8, v48
	v_mul_f32_e32 v48, v93, v53
	v_fmac_f32_e32 v48, v91, v49
	v_add_f32_e32 v46, v51, v46
	v_add_f32_e32 v47, v48, v47
	v_mul_f32_e32 v48, v11, v53
	v_add_f32_e32 v46, v50, v46
	v_fmac_f32_e32 v48, v9, v49
	v_add_f32_e32 v46, v48, v46
	s_waitcnt lgkmcnt(0)
; #define LAS __attribute__((address_space(3)))
; template <bool ZP, bool XF32, bool OUT8 = false>
; __device__ __forceinline__ void norm_phase(LAS unsigned char* lds, const void* xin, const float* gain, const float* sh, const float* sc, bf16* hout, const float* wzt, float* zout, int lane, int wave, int vcu, int G) {
;     ...
;         if constexpr (ZP) {
;             float p0[16], p1[16];
; #pragma unroll
;             for (int rr = 0; rr < 16; ++rr) { p0[rr] = 0.f; p1[rr] = 0.f;
; #pragma unroll
;                 for (int j = 0; j < 4; ++j) { const f32x4 w0 = *(const LAS f32x4*)(wl + (((rr * 4 + j) * 2 + 0) * 64 + lane) * 4), w1 = *(const LAS f32x4*)(wl + (((rr * 4 + j) * 2 + 1) * 64 + lane) * 4);
; #pragma unroll
;                     for (int e = 0; e < 4; ++e) { p0[rr] += v[0][j][0][e] * w0[e] + v[0][j][1][e] * w1[e]; p1[rr] += v[1][j][0][e] * w0[e] + v[1][j][1][e] * w1[e]; } } }
	v_mul_f32_e32 v48, v106, v124
	v_fmac_f32_e32 v48, v104, v54
	v_add_f32_e32 v47, v48, v47
	v_mul_f32_e32 v48, v20, v124
	v_fmac_f32_e32 v48, v18, v54
	v_add_f32_e32 v46, v48, v46
	v_mul_f32_e32 v48, v107, v125
	v_fmac_f32_e32 v48, v105, v55
	v_add_f32_e32 v47, v48, v47
	v_mul_f32_e32 v48, v21, v125
	v_fmac_f32_e32 v48, v19, v55
	v_add_f32_e32 v46, v48, v46
	v_mul_f32_e32 v48, v102, v126
	v_fmac_f32_e32 v48, v100, v56
	v_add_f32_e32 v54, v48, v47
	v_mul_f32_e32 v47, v6, v126
	v_fmac_f32_e32 v47, v16, v56
	v_add_f32_e32 v55, v47, v46
	ds_read_b128 v[46:49], v197
	ds_read_b128 v[50:53], v198
	v_mul_f32_e32 v56, v103, v127
	v_fmac_f32_e32 v56, v101, v57
	v_add_f32_e32 v129, v56, v54
	v_mul_f32_e32 v54, v7, v127
	v_fmac_f32_e32 v54, v17, v57
	v_add_f32_e32 v130, v54, v55
	s_waitcnt lgkmcnt(0)
	v_mul_f32_e32 v54, v82, v50
	v_mul_f32_e32 v50, v114, v50
	v_fmac_f32_e32 v50, v112, v46
	v_fmac_f32_e32 v54, v78, v46
	v_add_f32_e32 v46, 0, v50
	v_mul_f32_e32 v50, v83, v51
	v_mul_f32_e32 v51, v115, v51
	v_add_f32_e32 v54, 0, v54
	v_fmac_f32_e32 v50, v79, v47
	v_fmac_f32_e32 v51, v113, v47
	v_mul_f32_e32 v47, v76, v52
	v_add_f32_e32 v50, v50, v54
	v_fmac_f32_e32 v47, v74, v48
	v_add_f32_e32 v47, v47, v50
	v_mul_f32_e32 v50, v110, v52
	ds_read_b128 v[54:57], v199
	ds_read_b128 v[124:127], v200
	v_fmac_f32_e32 v50, v108, v48
	v_mul_f32_e32 v48, v77, v53
	v_fmac_f32_e32 v48, v75, v49
	v_add_f32_e32 v46, v51, v46
	v_add_f32_e32 v47, v48, v47
	v_mul_f32_e32 v48, v111, v53
	v_add_f32_e32 v46, v50, v46
	v_fmac_f32_e32 v48, v109, v49
	v_add_f32_e32 v46, v48, v46
	s_waitcnt lgkmcnt(0)
	v_mul_f32_e32 v48, v88, v124
	v_fmac_f32_e32 v48, v84, v54
	v_add_f32_e32 v47, v48, v47
	v_mul_f32_e32 v48, v122, v124
	v_fmac_f32_e32 v48, v120, v54
	v_add_f32_e32 v46, v48, v46
	v_mul_f32_e32 v48, v89, v125
	v_fmac_f32_e32 v48, v85, v55
	v_add_f32_e32 v47, v48, v47
	v_mul_f32_e32 v48, v123, v125
	v_fmac_f32_e32 v48, v121, v55
	v_add_f32_e32 v46, v48, v46
	v_mul_f32_e32 v48, v86, v126
	v_fmac_f32_e32 v48, v80, v56
	v_add_f32_e32 v54, v48, v47
	v_mul_f32_e32 v47, v118, v126
	v_fmac_f32_e32 v47, v116, v56
	v_add_f32_e32 v55, v47, v46
	ds_read_b128 v[46:49], v201
	ds_read_b128 v[50:53], v202
	v_mul_f32_e32 v56, v87, v127
	v_fmac_f32_e32 v56, v81, v57
	v_add_f32_e32 v54, v56, v54
	v_mul_f32_e32 v56, v119, v127
	v_fmac_f32_e32 v56, v117, v57
	v_add_f32_e32 v55, v56, v55
	s_waitcnt lgkmcnt(0)
	v_mul_f32_e32 v56, v96, v50
	v_mul_f32_e32 v50, v14, v50
	v_fmac_f32_e32 v50, v12, v46
	v_fmac_f32_e32 v56, v94, v46
	v_add_f32_e32 v46, v50, v55
	v_mul_f32_e32 v50, v97, v51
	v_mul_f32_e32 v51, v15, v51
	v_add_f32_e32 v54, v56, v54
	v_fmac_f32_e32 v50, v95, v47
	v_fmac_f32_e32 v51, v13, v47
	v_mul_f32_e32 v47, v92, v52
	v_add_f32_e32 v50, v50, v54
	v_fmac_f32_e32 v47, v90, v48
	v_add_f32_e32 v47, v47, v50
	v_mul_f32_e32 v50, v10, v52
	ds_read_b128 v[54:57], v203
	ds_read_b128 v[124:127], v204
	v_fmac_f32_e32 v50, v8, v48
	v_mul_f32_e32 v48, v93, v53
	v_fmac_f32_e32 v48, v91, v49
	v_add_f32_e32 v46, v51, v46
	v_add_f32_e32 v47, v48, v47
	v_mul_f32_e32 v48, v11, v53
	v_add_f32_e32 v46, v50, v46
	v_fmac_f32_e32 v48, v9, v49
	v_add_f32_e32 v46, v48, v46
	s_waitcnt lgkmcnt(0)
	v_mul_f32_e32 v48, v106, v124
	v_fmac_f32_e32 v48, v104, v54
	v_add_f32_e32 v47, v48, v47
	v_mul_f32_e32 v48, v20, v124
	v_fmac_f32_e32 v48, v18, v54
	v_add_f32_e32 v46, v48, v46
	v_mul_f32_e32 v48, v107, v125
	v_fmac_f32_e32 v48, v105, v55
	v_add_f32_e32 v47, v48, v47
	v_mul_f32_e32 v48, v21, v125
	v_fmac_f32_e32 v48, v19, v55
	v_add_f32_e32 v46, v48, v46
	v_mul_f32_e32 v48, v102, v126
	v_fmac_f32_e32 v48, v100, v56
	v_add_f32_e32 v54, v48, v47
	v_mul_f32_e32 v47, v6, v126
	v_fmac_f32_e32 v47, v16, v56
	v_add_f32_e32 v55, v47, v46
	ds_read_b128 v[46:49], v205
	ds_read_b128 v[50:53], v206
	v_mul_f32_e32 v56, v103, v127
	v_fmac_f32_e32 v56, v101, v57
	v_add_f32_e32 v124, v56, v54
	v_mul_f32_e32 v54, v7, v127
	v_fmac_f32_e32 v54, v17, v57
	v_add_f32_e32 v125, v54, v55
	s_waitcnt lgkmcnt(0)
	v_mul_f32_e32 v54, v82, v50
	v_mul_f32_e32 v50, v114, v50
	v_fmac_f32_e32 v50, v112, v46
	v_fmac_f32_e32 v54, v78, v46
	v_add_f32_e32 v46, 0, v50
	v_mul_f32_e32 v50, v83, v51
	v_mul_f32_e32 v51, v115, v51
	v_add_f32_e32 v54, 0, v54
	v_fmac_f32_e32 v50, v79, v47
	v_fmac_f32_e32 v51, v113, v47
	v_mul_f32_e32 v47, v76, v52
	v_add_f32_e32 v50, v50, v54
	v_fmac_f32_e32 v47, v74, v48
	v_add_f32_e32 v47, v47, v50
	v_mul_f32_e32 v50, v110, v52
	v_fmac_f32_e32 v50, v108, v48
	v_mul_f32_e32 v48, v77, v53
	v_fmac_f32_e32 v48, v75, v49
	ds_read_b128 v[54:57], v207
	ds_read_b128 v[74:77], v208
	v_add_f32_e32 v46, v51, v46
	v_add_f32_e32 v47, v48, v47
	v_mul_f32_e32 v48, v111, v53
	v_add_f32_e32 v46, v50, v46
	v_fmac_f32_e32 v48, v109, v49
	v_add_f32_e32 v46, v48, v46
	s_waitcnt lgkmcnt(0)
	v_mul_f32_e32 v48, v88, v74
	v_fmac_f32_e32 v48, v84, v54
	v_add_f32_e32 v47, v48, v47
	v_mul_f32_e32 v48, v122, v74
	v_fmac_f32_e32 v48, v120, v54
	v_add_f32_e32 v46, v48, v46
	v_mul_f32_e32 v48, v89, v75
	v_fmac_f32_e32 v48, v85, v55
	v_add_f32_e32 v47, v48, v47
	v_mul_f32_e32 v48, v123, v75
	v_fmac_f32_e32 v48, v121, v55
	v_add_f32_e32 v46, v48, v46
	v_mul_f32_e32 v48, v86, v76
	v_fmac_f32_e32 v48, v80, v56
	v_add_f32_e32 v54, v48, v47
	v_mul_f32_e32 v47, v118, v76
	v_fmac_f32_e32 v47, v116, v56
	v_add_f32_e32 v55, v47, v46
	ds_read_b128 v[46:49], v209
	ds_read_b128 v[50:53], v210
	v_mul_f32_e32 v56, v87, v77
	v_fmac_f32_e32 v56, v81, v57
	v_add_f32_e32 v54, v56, v54
	v_mul_f32_e32 v56, v119, v77
	v_fmac_f32_e32 v56, v117, v57
	s_waitcnt lgkmcnt(0)
; __device__ __forceinline__ float reduce16(const float (&p)[16], int lane) {
;     float a[8], b[4], c[2];
;     { const bool hi = (lane & 32) != 0;
; #pragma unroll
;       for (int k = 0; k < 8; ++k) { const float send = hi ? p[k] : p[k + 8], keep = hi ? p[k + 8] : p[k]; a[k] = keep + __shfl_xor(send, 32); } }
;     { const bool hi = (lane & 16) != 0;
; #pragma unroll
;       for (int k = 0; k < 4; ++k) { const float send = hi ? a[k] : a[k + 4], keep = hi ? a[k + 4] : a[k]; b[k] = keep + __shfl_xor(send, 16); } }
;     { const bool hi = (lane & 8) != 0;
; #pragma unroll
;       for (int k = 0; k < 2; ++k) { const float send = hi ? b[k] : b[k + 2], keep = hi ? b[k + 2] : b[k]; c[k] = keep + __shfl_xor(send, 8); } }
;     const bool hi4 = (lane & 4) != 0; const float send = hi4 ? c[0] : c[1], keep = hi4 ? c[1] : c[0];
;     float d = keep + __shfl_xor(send, 4);
;     d += __shfl_xor(d, 2); d += __shfl_xor(d, 1);
;     return d;
; template <bool ZP, bool XF32, bool OUT8 = false>
; __device__ __forceinline__ void norm_phase(LAS unsigned char* lds, const void* xin, const float* gain, const float* sh, const float* sc, bf16* hout, const float* wzt, float* zout, int lane, int wave, int vcu, int G) {
;     ...
;                     for (int e = 0; e < 4; ++e) { p0[rr] += v[0][j][0][e] * w0[e] + v[0][j][1][e] * w1[e]; p1[rr] += v[1][j][0][e] * w0[e] + v[1][j][1][e] * w1[e]; } } }
;             const float z0 = reduce16(p0, lane), z1 = reduce16(p1, lane);
;             if ((lane & 3) == 0) { const int rr = ((lane >> 5) & 1) * 8 + ((lane >> 4) & 1) * 4 + ((lane >> 3) & 1) * 2 + ((lane >> 2) & 1);
;                 zout[(size_t)m0 * 16 + rr] = z0; zout[(size_t)(m0 + 1) * 16 + rr] = z1; }
	v_mul_f32_e32 v14, v14, v50
	v_add_f32_e32 v55, v56, v55
	v_mul_f32_e32 v56, v96, v50
	v_fmac_f32_e32 v14, v12, v46
	v_fmac_f32_e32 v56, v94, v46
	v_add_f32_e32 v12, v14, v55
	v_mul_f32_e32 v14, v97, v51
	v_mul_f32_e32 v15, v15, v51
	v_add_f32_e32 v54, v56, v54
	v_fmac_f32_e32 v14, v95, v47
	v_fmac_f32_e32 v15, v13, v47
	v_mul_f32_e32 v13, v92, v52
	v_mul_f32_e32 v10, v10, v52
	v_add_f32_e32 v14, v14, v54
	v_add_f32_e32 v12, v15, v12
	v_fmac_f32_e32 v13, v90, v48
	v_fmac_f32_e32 v10, v8, v48
	v_add_f32_e32 v46, v13, v14
	v_add_f32_e32 v8, v10, v12
	ds_read_b128 v[12:15], v211
	ds_read_b128 v[54:57], v212
	v_mul_f32_e32 v10, v93, v53
	v_mul_f32_e32 v11, v11, v53
	v_fmac_f32_e32 v10, v91, v49
	v_fmac_f32_e32 v11, v9, v49
	s_waitcnt lgkmcnt(0)
	v_mul_f32_e32 v9, v106, v54
	v_add_f32_e32 v10, v10, v46
	v_fmac_f32_e32 v9, v104, v12
	v_add_f32_e32 v9, v9, v10
	v_mul_f32_e32 v10, v20, v54
	v_add_f32_e32 v8, v11, v8
	v_fmac_f32_e32 v10, v18, v12
	v_add_f32_e32 v8, v10, v8
	v_mul_f32_e32 v10, v107, v55
	v_fmac_f32_e32 v10, v105, v13
	v_add_f32_e32 v9, v10, v9
	v_mul_f32_e32 v10, v21, v55
	v_cndmask_b32_e64 v11, v5, v38, s[6:7]
	v_fmac_f32_e32 v10, v19, v13
	ds_bpermute_b32 v11, v222, v11
	v_cndmask_b32_e64 v12, v24, v40, s[6:7]
	v_add_f32_e32 v8, v10, v8
	v_mul_f32_e32 v10, v102, v56
	ds_bpermute_b32 v12, v222, v12
	v_cndmask_b32_e64 v13, v26, v42, s[6:7]
	v_fmac_f32_e32 v10, v100, v14
	ds_bpermute_b32 v13, v222, v13
	v_add_f32_e32 v9, v10, v9
	v_mul_f32_e32 v10, v6, v56
	v_fmac_f32_e32 v10, v16, v14
	v_cndmask_b32_e64 v5, v38, v5, s[6:7]
	v_add_f32_e32 v8, v10, v8
	v_mul_f32_e32 v10, v103, v57
	s_waitcnt lgkmcnt(2)
	v_add_f32_e32 v5, v5, v11
	v_cndmask_b32_e64 v11, v40, v24, s[6:7]
	v_fmac_f32_e32 v10, v101, v15
	s_waitcnt lgkmcnt(1)
	v_add_f32_e32 v11, v11, v12
	v_cndmask_b32_e64 v12, v42, v26, s[6:7]
	v_add_f32_e32 v9, v10, v9
	v_mul_f32_e32 v10, v7, v57
	s_waitcnt lgkmcnt(0)
	v_add_f32_e32 v12, v12, v13
	v_cndmask_b32_e64 v13, v28, v44, s[6:7]
	v_fmac_f32_e32 v10, v17, v15
	ds_bpermute_b32 v13, v222, v13
	v_cndmask_b32_e64 v15, v30, v128, s[6:7]
	ds_bpermute_b32 v15, v222, v15
	v_cndmask_b32_e64 v16, v32, v129, s[6:7]
	ds_bpermute_b32 v16, v222, v16
	v_cndmask_b32_e64 v14, v44, v28, s[6:7]
	s_waitcnt lgkmcnt(2)
	v_add_f32_e32 v13, v14, v13
	v_cndmask_b32_e64 v14, v128, v30, s[6:7]
	s_waitcnt lgkmcnt(1)
	v_add_f32_e32 v14, v14, v15
	v_cndmask_b32_e64 v15, v129, v32, s[6:7]
	s_waitcnt lgkmcnt(0)
	v_add_f32_e32 v15, v15, v16
	v_cndmask_b32_e64 v16, v34, v124, s[6:7]
	ds_bpermute_b32 v16, v222, v16
	v_cndmask_b32_e64 v18, v36, v9, s[6:7]
	ds_bpermute_b32 v18, v222, v18
	v_cndmask_b32_e64 v17, v124, v34, s[6:7]
	v_cndmask_b32_e64 v9, v9, v36, s[6:7]
	s_waitcnt lgkmcnt(1)
	v_add_f32_e32 v16, v17, v16
	v_cndmask_b32_e64 v19, v5, v14, s[8:9]
	s_waitcnt lgkmcnt(0)
	v_add_f32_e32 v9, v9, v18
	v_cndmask_b32_e64 v5, v14, v5, s[8:9]
	v_cndmask_b32_e64 v14, v11, v15, s[8:9]
	v_cndmask_b32_e64 v11, v15, v11, s[8:9]
	v_cndmask_b32_e64 v15, v12, v16, s[8:9]
	ds_bpermute_b32 v19, v221, v19
	ds_bpermute_b32 v15, v221, v15
	v_cndmask_b32_e64 v17, v13, v9, s[8:9]
	ds_bpermute_b32 v14, v221, v14
	ds_bpermute_b32 v17, v221, v17
	v_cndmask_b32_e64 v12, v16, v12, s[8:9]
	s_waitcnt lgkmcnt(3)
	v_add_f32_e32 v5, v5, v19
	s_waitcnt lgkmcnt(2)
	v_add_f32_e32 v12, v12, v15
	v_cndmask_b32_e64 v9, v9, v13, s[8:9]
	s_waitcnt lgkmcnt(1)
	v_add_f32_e32 v11, v11, v14
	s_waitcnt lgkmcnt(0)
	v_add_f32_e32 v9, v9, v17
	v_cndmask_b32_e64 v13, v5, v12, s[10:11]
	ds_bpermute_b32 v13, v220, v13
	v_cndmask_b32_e64 v14, v11, v9, s[10:11]
	ds_bpermute_b32 v14, v220, v14
	v_cndmask_b32_e64 v5, v12, v5, s[10:11]
	v_cndmask_b32_e64 v9, v9, v11, s[10:11]
	v_cndmask_b32_e64 v11, v22, v37, s[6:7]
	s_waitcnt lgkmcnt(1)
	v_add_f32_e32 v5, v5, v13
	ds_bpermute_b32 v11, v222, v11
	v_cndmask_b32_e64 v13, v23, v39, s[6:7]
	s_waitcnt lgkmcnt(1)
	v_add_f32_e32 v9, v9, v14
	ds_bpermute_b32 v13, v222, v13
	v_cndmask_b32_e64 v14, v25, v41, s[6:7]
	ds_bpermute_b32 v14, v222, v14
	v_cndmask_b32_e64 v12, v37, v22, s[6:7]
	s_waitcnt lgkmcnt(2)
	v_add_f32_e32 v11, v12, v11
	v_cndmask_b32_e64 v12, v39, v23, s[6:7]
	s_waitcnt lgkmcnt(1)
	v_add_f32_e32 v12, v12, v13
	v_cndmask_b32_e64 v13, v41, v25, s[6:7]
	s_waitcnt lgkmcnt(0)
	v_add_f32_e32 v13, v13, v14
	v_cndmask_b32_e64 v14, v27, v43, s[6:7]
	ds_bpermute_b32 v14, v222, v14
	v_cndmask_b32_e64 v16, v29, v45, s[6:7]
	ds_bpermute_b32 v16, v222, v16
	v_cndmask_b32_e64 v17, v31, v130, s[6:7]
	ds_bpermute_b32 v17, v222, v17
	v_cndmask_b32_e64 v15, v43, v27, s[6:7]
	s_waitcnt lgkmcnt(2)
	v_add_f32_e32 v14, v15, v14
	v_cndmask_b32_e64 v15, v45, v29, s[6:7]
	v_add_f32_e32 v8, v10, v8
	s_waitcnt lgkmcnt(1)
	v_add_f32_e32 v15, v15, v16
	v_cndmask_b32_e64 v16, v130, v31, s[6:7]
	s_waitcnt lgkmcnt(0)
	v_add_f32_e32 v16, v16, v17
	v_cndmask_b32_e64 v17, v33, v125, s[6:7]
	v_cndmask_b32_e64 v19, v35, v8, s[6:7]
	ds_bpermute_b32 v17, v222, v17
	ds_bpermute_b32 v19, v222, v19
	v_cndmask_b32_e64 v18, v125, v33, s[6:7]
	v_cndmask_b32_e64 v8, v8, v35, s[6:7]
	v_cndmask_b32_e64 v20, v11, v15, s[8:9]
	s_waitcnt lgkmcnt(1)
	v_add_f32_e32 v17, v18, v17
	s_waitcnt lgkmcnt(0)
	v_add_f32_e32 v8, v8, v19
	v_cndmask_b32_e64 v11, v15, v11, s[8:9]
	v_cndmask_b32_e64 v15, v12, v16, s[8:9]
	v_cndmask_b32_e64 v12, v16, v12, s[8:9]
	v_cndmask_b32_e64 v16, v13, v17, s[8:9]
	v_cndmask_b32_e64 v18, v14, v8, s[8:9]
	ds_bpermute_b32 v20, v221, v20
	ds_bpermute_b32 v15, v221, v15
	ds_bpermute_b32 v16, v221, v16
	ds_bpermute_b32 v18, v221, v18
	v_cndmask_b32_e64 v13, v17, v13, s[8:9]
	v_cndmask_b32_e64 v8, v8, v14, s[8:9]
	s_waitcnt lgkmcnt(3)
	v_add_f32_e32 v11, v11, v20
	s_waitcnt lgkmcnt(2)
	v_add_f32_e32 v12, v12, v15
	s_waitcnt lgkmcnt(1)
	v_add_f32_e32 v13, v13, v16
	s_waitcnt lgkmcnt(0)
	v_add_f32_e32 v8, v8, v18
	v_cndmask_b32_e64 v14, v11, v13, s[10:11]
	v_cndmask_b32_e64 v15, v12, v8, s[10:11]
	ds_bpermute_b32 v14, v220, v14
	ds_bpermute_b32 v15, v220, v15
	v_cndmask_b32_e64 v11, v13, v11, s[10:11]
	v_cndmask_b32_e64 v8, v8, v12, s[10:11]
	v_cndmask_b32_e64 v10, v5, v9, s[12:13]
	s_waitcnt lgkmcnt(1)
	v_add_f32_e32 v11, v11, v14
	s_waitcnt lgkmcnt(0)
	v_add_f32_e32 v8, v8, v15
	v_cndmask_b32_e64 v12, v11, v8, s[12:13]
	ds_bpermute_b32 v10, v219, v10
	ds_bpermute_b32 v12, v219, v12
	v_cndmask_b32_e64 v5, v9, v5, s[12:13]
	v_cndmask_b32_e64 v8, v8, v11, s[12:13]
	v_bfe_u32 v1, v6, 16, 1
	s_waitcnt lgkmcnt(1)
	v_add_f32_e32 v5, v5, v10
	s_waitcnt lgkmcnt(0)
	v_add_f32_e32 v8, v8, v12
	ds_bpermute_b32 v9, v218, v5
	ds_bpermute_b32 v10, v218, v8
	v_add3_u32 v1, v6, v1, s41
	v_lshrrev_b32_e32 v11, 16, v1
	s_waitcnt lgkmcnt(1)
	v_add_f32_e32 v1, v5, v9
	s_waitcnt lgkmcnt(0)
	v_add_f32_e32 v8, v8, v10
	ds_bpermute_b32 v6, v217, v1
	ds_bpermute_b32 v9, v217, v8
	v_bfe_u32 v5, v7, 16, 1
	v_add3_u32 v5, v7, v5, s41
	v_and_or_b32 v5, v5, s39, v11
	global_store_dwordx4 v[98:99], v[2:5], off offset:3072
	s_and_saveexec_b64 s[22:23], s[14:15]
	s_cbranch_execz .LBB0_1552
; template <bool ZP, bool XF32, bool OUT8 = false>
; __device__ __forceinline__ void norm_phase(LAS unsigned char* lds, const void* xin, const float* gain, const float* sh, const float* sc, bf16* hout, const float* wzt, float* zout, int lane, int wave, int vcu, int G) {
;     ...
;             const float z0 = reduce16(p0, lane), z1 = reduce16(p1, lane);
;             if ((lane & 3) == 0) { const int rr = ((lane >> 5) & 1) * 8 + ((lane >> 4) & 1) * 4 + ((lane >> 3) & 1) * 2 + ((lane >> 2) & 1);
;                 zout[(size_t)m0 * 16 + rr] = z0; zout[(size_t)(m0 + 1) * 16 + rr] = z1; }
	s_lshl_b64 s[0:1], s[18:19], 6
	s_waitcnt lgkmcnt(1)
	v_add_f32_e32 v1, v1, v6
	v_lshl_add_u64 v[2:3], v[60:61], 0, s[0:1]
	s_lshl_b64 s[0:1], s[20:21], 6
	s_waitcnt lgkmcnt(0)
	v_add_f32_e32 v4, v8, v9
	global_store_dword v[2:3], v1, off
	v_lshl_add_u64 v[2:3], v[60:61], 0, s[0:1]
	global_store_dword v[2:3], v4, off
	s_branch .LBB0_1552
